# st1 epilogue reuses rv rows kept in registers from the prologue (32 fewer ushort loads per thread per channel); early-H e=1 regs moved to v150-167
# baseline (speedup 1.0000x reference)
; __device__ __forceinline__ void fft_mid(float2* Z, const f16x2* Hp, int tid){
;   _Pragma("unroll 4") for (int i=0;i<8;++i){ int base=(tid<<2)+i*2048;
;     u32x4 hw=*(const u32x4*)(Hp+base);
; __device__ __forceinline__ void phase_hyena(KP kp_, int hf){ asm volatile("" : "+s"(kp_)); const Params p=load_params(kp_);
;     ...
;         const f16x2* Hp = st==1 ? H0p : H1p;
.Lmy_pf_skipb:
	s_cmp_eq_u32 s89, 0
	s_cbranch_scc1 .Lmy_noH
	s_cmp_eq_u32 s89, 1
	s_cselect_b32 s98, s76, s78
	s_cselect_b32 s99, s77, s79
	v_lshrrev_b32_e32 v222, 6, v154
	v_bfe_u32 v223, v154, 4, 2
	v_lshlrev_b32_e32 v222, 8, v222
	v_lshl_add_u32 v222, v223, 11, v222
	v_and_b32_e32 v223, 15, v154
	v_lshl_add_u32 v222, v223, 4, v222
	v_lshlrev_b32_e32 v222, 2, v222
	global_load_dwordx4 v[170:173], v222, s[98:99] offset:0 sc1
	global_load_dwordx4 v[174:177], v222, s[98:99] offset:16 sc1
	global_load_dwordx4 v[178:181], v222, s[98:99] offset:32 sc1
	global_load_dwordx4 v[182:185], v222, s[98:99] offset:48 sc1
	v_add_u32_e32 v223, 0x8000, v222
	global_load_dwordx4 v[150:153], v223, s[98:99] offset:0 sc1
	global_load_dwordx4 v[156:159], v223, s[98:99] offset:16 sc1
	global_load_dwordx4 v[160:163], v223, s[98:99] offset:32 sc1
	global_load_dwordx4 v[164:167], v223, s[98:99] offset:48 sc1

; HD float2 cmul(float2 a, float2 b){ return make_float2(a.x*b.x - a.y*b.y, a.x*b.y + a.y*b.x); }
; HD float2 cmulc(float2 a, float2 b){ return make_float2(a.x*b.x + a.y*b.y, a.y*b.x - a.x*b.y); }
; template<bool INV, bool NOTW>
; HD void bf4c(float2* Z, int i0, int i1, int i2, int i3, float2 w1, float2 w2, float2 w3){
;   float2 a0=Z[i0], a1=Z[i1], a2=Z[i2], a3=Z[i3];
;   if (INV && !NOTW){ a1=cmulc(a1,w1); a2=cmulc(a2,w2); a3=cmulc(a3,w3); }
;   float2 s02=make_float2(a0.x+a2.x,a0.y+a2.y), d02=make_float2(a0.x-a2.x,a0.y-a2.y);
;   float2 s13=make_float2(a1.x+a3.x,a1.y+a3.y), d13=make_float2(a1.x-a3.x,a1.y-a3.y);
;   float2 y0=make_float2(s02.x+s13.x,s02.y+s13.y), y2=make_float2(s02.x-s13.x,s02.y-s13.y);
;   float2 ym=make_float2(d02.x+d13.y,d02.y-d13.x);
;   float2 yp=make_float2(d02.x-d13.y,d02.y+d13.x);
;   float2 y1, y3;
;   if (INV){ y1=yp; y3=ym; } else if (NOTW){ y1=ym; y3=yp; } else { y1=cmul(ym,w1); y2=cmul(y2,w2); y3=cmul(yp,w3); }
;   Z[i0]=y0; Z[i1]=y1; Z[i2]=y2; Z[i3]=y3;
; }
; template<bool INV, int LQ, bool BARRIER=true>
; HD void fft_pass(float2* Z, const float2* twA, const float2* twB, int tid){
;     ...
;     int j=tid&(q-1); int base0=((tid>>LQ)<<(LQ+2))+j;
;     float2 w1=make_float2(1.f,0.f), w2=w1, w3=w1;
;     if (LQ>0){ int k=j*tws; w1=cmul(twA[k>>6],twB[k&63]); w2=cmul(w1,w1); w3=cmul(w2,w1); }
;     _Pragma("unroll") for (int i=0;i<8;++i){ int base=base0+i*2048; bf4c<INV,(LQ==0)>(Z,base,base+q,base+2*q,base+3*q,w1,w2,w3); }
.Lmy_skip_lq2:
	v_add_u32_e32 v14, 0x4000, v169
	v_add_u32_e32 v15, 0x8000, v169
	v_add_u32_e32 v16, 0xc000, v169
	v_add_u32_e32 v17, 0x4000, v186
	v_add_u32_e32 v18, 0x8000, v186
	v_add_u32_e32 v19, 0xc000, v186
	s_mov_b64 s[12:13], -1
	s_and_b64 vcc, exec, s[68:69]
	s_cbranch_vccz .LBB0_1344
	s_cmp_lg_u32 s89, 1
	s_cselect_b64 s[50:51], -1, 0
	s_cmp_eq_u32 s89, 1
	s_cselect_b32 s69, s77, s79
	s_cselect_b32 s68, s76, s78
	v_mov_b32_e32 v68, 0x3f6c835e
	v_mov_b32_e32 v69, 0x3ec3ef15
	v_mov_b32_e32 v70, 0x3f3504f3
	v_mov_b32_e32 v71, 0x3f3504f3
	v_lshrrev_b32_e32 v225, 6, v154
	v_bfe_u32 v226, v154, 4, 2
	v_lshlrev_b32_e32 v225, 8, v225
	v_lshl_add_u32 v225, v226, 11, v225
	v_and_b32_e32 v226, 15, v154
	v_lshl_add_u32 v225, v226, 4, v225
	v_lshlrev_b32_e32 v222, 3, v225
	v_add_u32_e32 v223, 0x10000, v222
	v_lshlrev_b32_e32 v224, 2, v225
	v_bfe_u32 v225, v154, 1, 1
	v_cmp_eq_u32_e64 s[98:99], 1, v225
	v_lshlrev_b32_e32 v225, 4, v225
	s_nop 3
	v_add_u32_e32 v74, v222, v225
	v_sub_u32_e32 v75, v222, v225
	v_add_u32_e32 v80, v222, v225
	v_sub_u32_e32 v81, v222, v225
	ds_read_b128 v[0:3], v74 offset:0
	ds_read_b128 v[4:7], v75 offset:16
	ds_read_b128 v[8:11], v80 offset:32
	ds_read_b128 v[12:15], v81 offset:48
	ds_read_b128 v[16:19], v74 offset:64
	ds_read_b128 v[20:23], v75 offset:80
	ds_read_b128 v[24:27], v80 offset:96
	ds_read_b128 v[28:31], v81 offset:112
	s_waitcnt lgkmcnt(0)
	s_mov_b64 exec, s[98:99]
	v_swap_b32 v0, v4
	v_swap_b32 v1, v5
	v_swap_b32 v2, v6
	v_swap_b32 v3, v7
	v_swap_b32 v8, v12
	v_swap_b32 v9, v13
	v_swap_b32 v10, v14
	v_swap_b32 v11, v15
	v_swap_b32 v16, v20
	v_swap_b32 v17, v21
	v_swap_b32 v18, v22
	v_swap_b32 v19, v23
	v_swap_b32 v24, v28
	v_swap_b32 v25, v29
	v_swap_b32 v26, v30
	v_swap_b32 v27, v31
	s_mov_b64 exec, -1
	v_pk_add_f32 v[58:59], v[0:1], v[16:17]
	v_pk_add_f32 v[60:61], v[0:1], v[16:17] neg_lo:[0,1] neg_hi:[0,1]
	v_pk_add_f32 v[62:63], v[8:9], v[24:25]
	v_pk_add_f32 v[64:65], v[8:9], v[24:25] neg_lo:[0,1] neg_hi:[0,1]
	v_pk_add_f32 v[0:1], v[58:59], v[62:63]
	v_pk_add_f32 v[16:17], v[58:59], v[62:63] neg_lo:[0,1] neg_hi:[0,1]
	v_pk_add_f32 v[8:9], v[60:61], v[64:65] op_sel:[0,1] op_sel_hi:[1,0] neg_hi:[0,1]
	v_pk_add_f32 v[24:25], v[60:61], v[64:65] op_sel:[0,1] op_sel_hi:[1,0] neg_lo:[0,1]
	v_pk_add_f32 v[58:59], v[2:3], v[18:19]
	v_pk_add_f32 v[60:61], v[2:3], v[18:19] neg_lo:[0,1] neg_hi:[0,1]
	v_pk_add_f32 v[62:63], v[10:11], v[26:27]
	v_pk_add_f32 v[64:65], v[10:11], v[26:27] neg_lo:[0,1] neg_hi:[0,1]
	v_pk_add_f32 v[2:3], v[58:59], v[62:63]
	v_pk_add_f32 v[18:19], v[58:59], v[62:63] neg_lo:[0,1] neg_hi:[0,1]
	v_pk_add_f32 v[10:11], v[60:61], v[64:65] op_sel:[0,1] op_sel_hi:[1,0] neg_hi:[0,1]
	v_pk_add_f32 v[26:27], v[60:61], v[64:65] op_sel:[0,1] op_sel_hi:[1,0] neg_lo:[0,1]
	v_pk_mul_f32 v[66:67], v[10:11], v[68:69] op_sel:[1,1] op_sel_hi:[1,0] neg_lo:[0,1] neg_hi:[0,0]
	v_pk_fma_f32 v[10:11], v[10:11], v[68:69], v[66:67] op_sel:[0,0,0] op_sel_hi:[0,1,1] neg_lo:[0,0,1] neg_hi:[0,1,0]
	v_pk_mul_f32 v[66:67], v[18:19], v[70:71] op_sel:[1,1] op_sel_hi:[1,0] neg_lo:[0,1] neg_hi:[0,0]
	v_pk_fma_f32 v[18:19], v[18:19], v[70:71], v[66:67] op_sel:[0,0,0] op_sel_hi:[0,1,1] neg_lo:[0,0,1] neg_hi:[0,1,0]
	v_pk_mul_f32 v[66:67], v[26:27], v[68:69] op_sel:[1,0] op_sel_hi:[1,1] neg_lo:[0,1] neg_hi:[0,0]
	v_pk_fma_f32 v[26:27], v[26:27], v[68:69], v[66:67] op_sel:[0,1,0] op_sel_hi:[0,0,1] neg_lo:[0,0,1] neg_hi:[0,1,0]
	v_pk_add_f32 v[58:59], v[4:5], v[20:21]
	v_pk_add_f32 v[60:61], v[4:5], v[20:21] neg_lo:[0,1] neg_hi:[0,1]
	v_pk_add_f32 v[62:63], v[12:13], v[28:29]
	v_pk_add_f32 v[64:65], v[12:13], v[28:29] neg_lo:[0,1] neg_hi:[0,1]
	v_pk_add_f32 v[4:5], v[58:59], v[62:63]
	v_pk_add_f32 v[20:21], v[58:59], v[62:63] neg_lo:[0,1] neg_hi:[0,1]
	v_pk_add_f32 v[12:13], v[60:61], v[64:65] op_sel:[0,1] op_sel_hi:[1,0] neg_hi:[0,1]
	v_pk_add_f32 v[28:29], v[60:61], v[64:65] op_sel:[0,1] op_sel_hi:[1,0] neg_lo:[0,1]
	v_pk_mul_f32 v[66:67], v[12:13], v[70:71] op_sel:[1,1] op_sel_hi:[1,0] neg_lo:[0,1] neg_hi:[0,0]
	v_pk_fma_f32 v[12:13], v[12:13], v[70:71], v[66:67] op_sel:[0,0,0] op_sel_hi:[0,1,1] neg_lo:[0,0,1] neg_hi:[0,1,0]
	v_pk_add_f32 v[20:21], v[20:21], 0 op_sel:[1,0] op_sel_hi:[0,0] neg_hi:[1,0]
	v_pk_mul_f32 v[66:67], v[28:29], v[70:71] op_sel:[1,1] op_sel_hi:[1,0] neg_lo:[0,1] neg_hi:[0,1]
	v_pk_fma_f32 v[28:29], v[28:29], v[70:71], v[66:67] op_sel:[0,0,0] op_sel_hi:[0,1,1] neg_lo:[0,1,1] neg_hi:[0,1,0]
	v_pk_add_f32 v[58:59], v[6:7], v[22:23]
	v_pk_add_f32 v[60:61], v[6:7], v[22:23] neg_lo:[0,1] neg_hi:[0,1]
	v_pk_add_f32 v[62:63], v[14:15], v[30:31]
	v_pk_add_f32 v[64:65], v[14:15], v[30:31] neg_lo:[0,1] neg_hi:[0,1]
	v_pk_add_f32 v[6:7], v[58:59], v[62:63]
	v_pk_add_f32 v[22:23], v[58:59], v[62:63] neg_lo:[0,1] neg_hi:[0,1]
	v_pk_add_f32 v[14:15], v[60:61], v[64:65] op_sel:[0,1] op_sel_hi:[1,0] neg_hi:[0,1]
	v_pk_add_f32 v[30:31], v[60:61], v[64:65] op_sel:[0,1] op_sel_hi:[1,0] neg_lo:[0,1]
	v_pk_mul_f32 v[66:67], v[14:15], v[68:69] op_sel:[1,0] op_sel_hi:[1,1] neg_lo:[0,1] neg_hi:[0,0]
	v_pk_fma_f32 v[14:15], v[14:15], v[68:69], v[66:67] op_sel:[0,1,0] op_sel_hi:[0,0,1] neg_lo:[0,0,1] neg_hi:[0,1,0]
	v_pk_mul_f32 v[66:67], v[22:23], v[70:71] op_sel:[1,1] op_sel_hi:[1,0] neg_lo:[0,1] neg_hi:[0,1]
	v_pk_fma_f32 v[22:23], v[22:23], v[70:71], v[66:67] op_sel:[0,0,0] op_sel_hi:[0,1,1] neg_lo:[0,1,1] neg_hi:[0,1,0]
	v_pk_mul_f32 v[66:67], v[30:31], v[68:69] op_sel:[1,1] op_sel_hi:[1,0] neg_lo:[0,0] neg_hi:[0,1]
	v_pk_fma_f32 v[30:31], v[30:31], v[68:69], v[66:67] op_sel:[0,0,0] op_sel_hi:[0,1,1] neg_lo:[0,1,1] neg_hi:[0,0,0]
	v_pk_add_f32 v[58:59], v[0:1], v[4:5]
	v_pk_add_f32 v[60:61], v[0:1], v[4:5] neg_lo:[0,1] neg_hi:[0,1]
; HD float2 cmul(float2 a, float2 b){ return make_float2(a.x*b.x - a.y*b.y, a.x*b.y + a.y*b.x); }
; __device__ __forceinline__ void fft_mid(float2* Z, const f16x2* Hp, int tid){
;   _Pragma("unroll 4") for (int i=0;i<8;++i){ int base=(tid<<2)+i*2048;
;     u32x4 hw=*(const u32x4*)(Hp+base);
;     unsigned hw0=hw[0], hw1=hw[1], hw2=hw[2], hw3=hw[3];
;     float2 a0=Z[base], a1=Z[base+1], a2=Z[base+2], a3=Z[base+3];
;     float2 s02=make_float2(a0.x+a2.x,a0.y+a2.y), d02=make_float2(a0.x-a2.x,a0.y-a2.y);
;     float2 s13=make_float2(a1.x+a3.x,a1.y+a3.y), d13=make_float2(a1.x-a3.x,a1.y-a3.y);
;     float2 y0=make_float2(s02.x+s13.x,s02.y+s13.y), y2=make_float2(s02.x-s13.x,s02.y-s13.y);
;     float2 y1=make_float2(d02.x+d13.y,d02.y-d13.x);
;     float2 y3=make_float2(d02.x-d13.y,d02.y+d13.x);
;     f16x2 h0=__builtin_bit_cast(f16x2,hw0), h1=__builtin_bit_cast(f16x2,hw1), h2=__builtin_bit_cast(f16x2,hw2), h3=__builtin_bit_cast(f16x2,hw3);
;     float2 b0=cmul(y0,make_float2((float)h0[0],(float)h0[1])), b1=cmul(y1,make_float2((float)h1[0],(float)h1[1]));
;     float2 b2=cmul(y2,make_float2((float)h2[0],(float)h2[1])), b3=cmul(y3,make_float2((float)h3[0],(float)h3[1]));
	v_pk_add_f32 v[62:63], v[2:3], v[6:7]
	v_pk_add_f32 v[64:65], v[2:3], v[6:7] neg_lo:[0,1] neg_hi:[0,1]
	v_pk_add_f32 v[0:1], v[58:59], v[62:63]
	v_pk_add_f32 v[4:5], v[58:59], v[62:63] neg_lo:[0,1] neg_hi:[0,1]
	v_pk_add_f32 v[2:3], v[60:61], v[64:65] op_sel:[0,1] op_sel_hi:[1,0] neg_hi:[0,1]
	v_pk_add_f32 v[6:7], v[60:61], v[64:65] op_sel:[0,1] op_sel_hi:[1,0] neg_lo:[0,1]
	v_pk_add_f32 v[58:59], v[8:9], v[12:13]
	v_pk_add_f32 v[60:61], v[8:9], v[12:13] neg_lo:[0,1] neg_hi:[0,1]
	v_pk_add_f32 v[62:63], v[10:11], v[14:15]
	v_pk_add_f32 v[64:65], v[10:11], v[14:15] neg_lo:[0,1] neg_hi:[0,1]
	v_pk_add_f32 v[8:9], v[58:59], v[62:63]
	v_pk_add_f32 v[12:13], v[58:59], v[62:63] neg_lo:[0,1] neg_hi:[0,1]
	v_pk_add_f32 v[10:11], v[60:61], v[64:65] op_sel:[0,1] op_sel_hi:[1,0] neg_hi:[0,1]
	v_pk_add_f32 v[14:15], v[60:61], v[64:65] op_sel:[0,1] op_sel_hi:[1,0] neg_lo:[0,1]
	v_pk_add_f32 v[58:59], v[16:17], v[20:21]
	v_pk_add_f32 v[60:61], v[16:17], v[20:21] neg_lo:[0,1] neg_hi:[0,1]
	v_pk_add_f32 v[62:63], v[18:19], v[22:23]
	v_pk_add_f32 v[64:65], v[18:19], v[22:23] neg_lo:[0,1] neg_hi:[0,1]
	v_pk_add_f32 v[16:17], v[58:59], v[62:63]
	v_pk_add_f32 v[20:21], v[58:59], v[62:63] neg_lo:[0,1] neg_hi:[0,1]
	v_pk_add_f32 v[18:19], v[60:61], v[64:65] op_sel:[0,1] op_sel_hi:[1,0] neg_hi:[0,1]
	v_pk_add_f32 v[22:23], v[60:61], v[64:65] op_sel:[0,1] op_sel_hi:[1,0] neg_lo:[0,1]
	v_pk_add_f32 v[58:59], v[24:25], v[28:29]
	v_pk_add_f32 v[60:61], v[24:25], v[28:29] neg_lo:[0,1] neg_hi:[0,1]
	v_pk_add_f32 v[62:63], v[26:27], v[30:31]
	v_pk_add_f32 v[64:65], v[26:27], v[30:31] neg_lo:[0,1] neg_hi:[0,1]
	v_pk_add_f32 v[24:25], v[58:59], v[62:63]
	v_pk_add_f32 v[28:29], v[58:59], v[62:63] neg_lo:[0,1] neg_hi:[0,1]
	v_pk_add_f32 v[26:27], v[60:61], v[64:65] op_sel:[0,1] op_sel_hi:[1,0] neg_hi:[0,1]
	v_pk_add_f32 v[30:31], v[60:61], v[64:65] op_sel:[0,1] op_sel_hi:[1,0] neg_lo:[0,1]
	s_waitcnt vmcnt(0)
	v_cvt_f32_f16_e32 v72, v170
	v_cvt_f32_f16_sdwa v73, v170 dst_sel:DWORD dst_unused:UNUSED_PAD src0_sel:WORD_1
	s_nop 0
	v_pk_mul_f32 v[66:67], v[0:1], v[72:73] op_sel:[1,1] op_sel_hi:[1,0]
	v_pk_fma_f32 v[0:1], v[0:1], v[72:73], v[66:67] op_sel:[0,0,0] op_sel_hi:[0,1,1] neg_lo:[0,0,1]
	v_cvt_f32_f16_e32 v72, v171
	v_cvt_f32_f16_sdwa v73, v171 dst_sel:DWORD dst_unused:UNUSED_PAD src0_sel:WORD_1
	s_nop 0
	v_pk_mul_f32 v[66:67], v[2:3], v[72:73] op_sel:[1,1] op_sel_hi:[1,0]
	v_pk_fma_f32 v[2:3], v[2:3], v[72:73], v[66:67] op_sel:[0,0,0] op_sel_hi:[0,1,1] neg_lo:[0,0,1]
	v_cvt_f32_f16_e32 v72, v172
	v_cvt_f32_f16_sdwa v73, v172 dst_sel:DWORD dst_unused:UNUSED_PAD src0_sel:WORD_1
	s_nop 0
	v_pk_mul_f32 v[66:67], v[4:5], v[72:73] op_sel:[1,1] op_sel_hi:[1,0]
	v_pk_fma_f32 v[4:5], v[4:5], v[72:73], v[66:67] op_sel:[0,0,0] op_sel_hi:[0,1,1] neg_lo:[0,0,1]
	v_cvt_f32_f16_e32 v72, v173
	v_cvt_f32_f16_sdwa v73, v173 dst_sel:DWORD dst_unused:UNUSED_PAD src0_sel:WORD_1
	s_nop 0
	v_pk_mul_f32 v[66:67], v[6:7], v[72:73] op_sel:[1,1] op_sel_hi:[1,0]
	v_pk_fma_f32 v[6:7], v[6:7], v[72:73], v[66:67] op_sel:[0,0,0] op_sel_hi:[0,1,1] neg_lo:[0,0,1]
	v_cvt_f32_f16_e32 v72, v174
	v_cvt_f32_f16_sdwa v73, v174 dst_sel:DWORD dst_unused:UNUSED_PAD src0_sel:WORD_1
	s_nop 0
	v_pk_mul_f32 v[66:67], v[8:9], v[72:73] op_sel:[1,1] op_sel_hi:[1,0]
	v_pk_fma_f32 v[8:9], v[8:9], v[72:73], v[66:67] op_sel:[0,0,0] op_sel_hi:[0,1,1] neg_lo:[0,0,1]
	v_cvt_f32_f16_e32 v72, v175
	v_cvt_f32_f16_sdwa v73, v175 dst_sel:DWORD dst_unused:UNUSED_PAD src0_sel:WORD_1
	s_nop 0
	v_pk_mul_f32 v[66:67], v[10:11], v[72:73] op_sel:[1,1] op_sel_hi:[1,0]
	v_pk_fma_f32 v[10:11], v[10:11], v[72:73], v[66:67] op_sel:[0,0,0] op_sel_hi:[0,1,1] neg_lo:[0,0,1]
	v_cvt_f32_f16_e32 v72, v176
	v_cvt_f32_f16_sdwa v73, v176 dst_sel:DWORD dst_unused:UNUSED_PAD src0_sel:WORD_1
	s_nop 0
	v_pk_mul_f32 v[66:67], v[12:13], v[72:73] op_sel:[1,1] op_sel_hi:[1,0]
	v_pk_fma_f32 v[12:13], v[12:13], v[72:73], v[66:67] op_sel:[0,0,0] op_sel_hi:[0,1,1] neg_lo:[0,0,1]
	v_cvt_f32_f16_e32 v72, v177
	v_cvt_f32_f16_sdwa v73, v177 dst_sel:DWORD dst_unused:UNUSED_PAD src0_sel:WORD_1
	s_nop 0
	v_pk_mul_f32 v[66:67], v[14:15], v[72:73] op_sel:[1,1] op_sel_hi:[1,0]
	v_pk_fma_f32 v[14:15], v[14:15], v[72:73], v[66:67] op_sel:[0,0,0] op_sel_hi:[0,1,1] neg_lo:[0,0,1]
	v_cvt_f32_f16_e32 v72, v178
	v_cvt_f32_f16_sdwa v73, v178 dst_sel:DWORD dst_unused:UNUSED_PAD src0_sel:WORD_1
	s_nop 0
	v_pk_mul_f32 v[66:67], v[16:17], v[72:73] op_sel:[1,1] op_sel_hi:[1,0]
	v_pk_fma_f32 v[16:17], v[16:17], v[72:73], v[66:67] op_sel:[0,0,0] op_sel_hi:[0,1,1] neg_lo:[0,0,1]
	v_cvt_f32_f16_e32 v72, v179
	v_cvt_f32_f16_sdwa v73, v179 dst_sel:DWORD dst_unused:UNUSED_PAD src0_sel:WORD_1
	s_nop 0
	v_pk_mul_f32 v[66:67], v[18:19], v[72:73] op_sel:[1,1] op_sel_hi:[1,0]
	v_pk_fma_f32 v[18:19], v[18:19], v[72:73], v[66:67] op_sel:[0,0,0] op_sel_hi:[0,1,1] neg_lo:[0,0,1]
	v_cvt_f32_f16_e32 v72, v180
	v_cvt_f32_f16_sdwa v73, v180 dst_sel:DWORD dst_unused:UNUSED_PAD src0_sel:WORD_1
	s_nop 0
	v_pk_mul_f32 v[66:67], v[20:21], v[72:73] op_sel:[1,1] op_sel_hi:[1,0]
	v_pk_fma_f32 v[20:21], v[20:21], v[72:73], v[66:67] op_sel:[0,0,0] op_sel_hi:[0,1,1] neg_lo:[0,0,1]
	v_cvt_f32_f16_e32 v72, v181
	v_cvt_f32_f16_sdwa v73, v181 dst_sel:DWORD dst_unused:UNUSED_PAD src0_sel:WORD_1
	s_nop 0
	v_pk_mul_f32 v[66:67], v[22:23], v[72:73] op_sel:[1,1] op_sel_hi:[1,0]
	v_pk_fma_f32 v[22:23], v[22:23], v[72:73], v[66:67] op_sel:[0,0,0] op_sel_hi:[0,1,1] neg_lo:[0,0,1]
	v_cvt_f32_f16_e32 v72, v182
	v_cvt_f32_f16_sdwa v73, v182 dst_sel:DWORD dst_unused:UNUSED_PAD src0_sel:WORD_1
	s_nop 0
	v_pk_mul_f32 v[66:67], v[24:25], v[72:73] op_sel:[1,1] op_sel_hi:[1,0]
	v_pk_fma_f32 v[24:25], v[24:25], v[72:73], v[66:67] op_sel:[0,0,0] op_sel_hi:[0,1,1] neg_lo:[0,0,1]
; HD float2 cmul(float2 a, float2 b){ return make_float2(a.x*b.x - a.y*b.y, a.x*b.y + a.y*b.x); }
; HD float2 cmulc(float2 a, float2 b){ return make_float2(a.x*b.x + a.y*b.y, a.y*b.x - a.x*b.y); }
; template<bool INV, bool NOTW>
; HD void bf4c(float2* Z, int i0, int i1, int i2, int i3, float2 w1, float2 w2, float2 w3){
;   float2 a0=Z[i0], a1=Z[i1], a2=Z[i2], a3=Z[i3];
;   if (INV && !NOTW){ a1=cmulc(a1,w1); a2=cmulc(a2,w2); a3=cmulc(a3,w3); }
;   float2 s02=make_float2(a0.x+a2.x,a0.y+a2.y), d02=make_float2(a0.x-a2.x,a0.y-a2.y);
;   float2 s13=make_float2(a1.x+a3.x,a1.y+a3.y), d13=make_float2(a1.x-a3.x,a1.y-a3.y);
;   float2 y0=make_float2(s02.x+s13.x,s02.y+s13.y), y2=make_float2(s02.x-s13.x,s02.y-s13.y);
;   float2 ym=make_float2(d02.x+d13.y,d02.y-d13.x);
;   float2 yp=make_float2(d02.x-d13.y,d02.y+d13.x);
;   float2 y1, y3;
;   if (INV){ y1=yp; y3=ym; } else if (NOTW){ y1=ym; y3=yp; } else { y1=cmul(ym,w1); y2=cmul(y2,w2); y3=cmul(yp,w3); }
;   Z[i0]=y0; Z[i1]=y1; Z[i2]=y2; Z[i3]=y3;
; }
; __device__ __forceinline__ void fft_mid(float2* Z, const f16x2* Hp, int tid){
;     ...
;     float2 t02=make_float2(b0.x+b2.x,b0.y+b2.y), e02=make_float2(b0.x-b2.x,b0.y-b2.y);
;     float2 t13=make_float2(b1.x+b3.x,b1.y+b3.y), e13=make_float2(b1.x-b3.x,b1.y-b3.y);
;     Z[base]=make_float2(t02.x+t13.x,t02.y+t13.y); Z[base+2]=make_float2(t02.x-t13.x,t02.y-t13.y);
;     Z[base+1]=make_float2(e02.x-e13.y,e02.y+e13.x);
;     Z[base+3]=make_float2(e02.x+e13.y,e02.y-e13.x);
	v_cvt_f32_f16_e32 v72, v183
	v_cvt_f32_f16_sdwa v73, v183 dst_sel:DWORD dst_unused:UNUSED_PAD src0_sel:WORD_1
	s_nop 0
	v_pk_mul_f32 v[66:67], v[26:27], v[72:73] op_sel:[1,1] op_sel_hi:[1,0]
	v_pk_fma_f32 v[26:27], v[26:27], v[72:73], v[66:67] op_sel:[0,0,0] op_sel_hi:[0,1,1] neg_lo:[0,0,1]
	v_cvt_f32_f16_e32 v72, v184
	v_cvt_f32_f16_sdwa v73, v184 dst_sel:DWORD dst_unused:UNUSED_PAD src0_sel:WORD_1
	s_nop 0
	v_pk_mul_f32 v[66:67], v[28:29], v[72:73] op_sel:[1,1] op_sel_hi:[1,0]
	v_pk_fma_f32 v[28:29], v[28:29], v[72:73], v[66:67] op_sel:[0,0,0] op_sel_hi:[0,1,1] neg_lo:[0,0,1]
	v_cvt_f32_f16_e32 v72, v185
	v_cvt_f32_f16_sdwa v73, v185 dst_sel:DWORD dst_unused:UNUSED_PAD src0_sel:WORD_1
	s_nop 0
	v_pk_mul_f32 v[66:67], v[30:31], v[72:73] op_sel:[1,1] op_sel_hi:[1,0]
	v_pk_fma_f32 v[30:31], v[30:31], v[72:73], v[66:67] op_sel:[0,0,0] op_sel_hi:[0,1,1] neg_lo:[0,0,1]
	v_pk_add_f32 v[58:59], v[0:1], v[4:5]
	v_pk_add_f32 v[60:61], v[0:1], v[4:5] neg_lo:[0,1] neg_hi:[0,1]
	v_pk_add_f32 v[62:63], v[2:3], v[6:7]
	v_pk_add_f32 v[64:65], v[2:3], v[6:7] neg_lo:[0,1] neg_hi:[0,1]
	v_pk_add_f32 v[0:1], v[58:59], v[62:63]
	v_pk_add_f32 v[4:5], v[58:59], v[62:63] neg_lo:[0,1] neg_hi:[0,1]
	v_pk_add_f32 v[2:3], v[60:61], v[64:65] op_sel:[0,1] op_sel_hi:[1,0] neg_lo:[0,1]
	v_pk_add_f32 v[6:7], v[60:61], v[64:65] op_sel:[0,1] op_sel_hi:[1,0] neg_hi:[0,1]
	v_pk_add_f32 v[58:59], v[8:9], v[12:13]
	v_pk_add_f32 v[60:61], v[8:9], v[12:13] neg_lo:[0,1] neg_hi:[0,1]
	v_pk_add_f32 v[62:63], v[10:11], v[14:15]
	v_pk_add_f32 v[64:65], v[10:11], v[14:15] neg_lo:[0,1] neg_hi:[0,1]
	v_pk_add_f32 v[8:9], v[58:59], v[62:63]
	v_pk_add_f32 v[12:13], v[58:59], v[62:63] neg_lo:[0,1] neg_hi:[0,1]
	v_pk_add_f32 v[10:11], v[60:61], v[64:65] op_sel:[0,1] op_sel_hi:[1,0] neg_lo:[0,1]
	v_pk_add_f32 v[14:15], v[60:61], v[64:65] op_sel:[0,1] op_sel_hi:[1,0] neg_hi:[0,1]
	v_pk_add_f32 v[58:59], v[16:17], v[20:21]
	v_pk_add_f32 v[60:61], v[16:17], v[20:21] neg_lo:[0,1] neg_hi:[0,1]
	v_pk_add_f32 v[62:63], v[18:19], v[22:23]
	v_pk_add_f32 v[64:65], v[18:19], v[22:23] neg_lo:[0,1] neg_hi:[0,1]
	v_pk_add_f32 v[16:17], v[58:59], v[62:63]
	v_pk_add_f32 v[20:21], v[58:59], v[62:63] neg_lo:[0,1] neg_hi:[0,1]
	v_pk_add_f32 v[18:19], v[60:61], v[64:65] op_sel:[0,1] op_sel_hi:[1,0] neg_lo:[0,1]
	v_pk_add_f32 v[22:23], v[60:61], v[64:65] op_sel:[0,1] op_sel_hi:[1,0] neg_hi:[0,1]
	v_pk_add_f32 v[58:59], v[24:25], v[28:29]
	v_pk_add_f32 v[60:61], v[24:25], v[28:29] neg_lo:[0,1] neg_hi:[0,1]
	v_pk_add_f32 v[62:63], v[26:27], v[30:31]
	v_pk_add_f32 v[64:65], v[26:27], v[30:31] neg_lo:[0,1] neg_hi:[0,1]
	v_pk_add_f32 v[24:25], v[58:59], v[62:63]
	v_pk_add_f32 v[28:29], v[58:59], v[62:63] neg_lo:[0,1] neg_hi:[0,1]
	v_pk_add_f32 v[26:27], v[60:61], v[64:65] op_sel:[0,1] op_sel_hi:[1,0] neg_lo:[0,1]
	v_pk_add_f32 v[30:31], v[60:61], v[64:65] op_sel:[0,1] op_sel_hi:[1,0] neg_hi:[0,1]
	v_pk_add_f32 v[58:59], v[0:1], v[16:17]
	v_pk_add_f32 v[60:61], v[0:1], v[16:17] neg_lo:[0,1] neg_hi:[0,1]
	v_pk_add_f32 v[62:63], v[8:9], v[24:25]
	v_pk_add_f32 v[64:65], v[8:9], v[24:25] neg_lo:[0,1] neg_hi:[0,1]
	v_pk_add_f32 v[0:1], v[58:59], v[62:63]
	v_pk_add_f32 v[16:17], v[58:59], v[62:63] neg_lo:[0,1] neg_hi:[0,1]
	v_pk_add_f32 v[8:9], v[60:61], v[64:65] op_sel:[0,1] op_sel_hi:[1,0] neg_lo:[0,1]
	v_pk_add_f32 v[24:25], v[60:61], v[64:65] op_sel:[0,1] op_sel_hi:[1,0] neg_hi:[0,1]
	v_pk_mul_f32 v[66:67], v[10:11], v[68:69] op_sel:[1,1] op_sel_hi:[1,0] neg_lo:[0,0] neg_hi:[0,0]
	v_pk_fma_f32 v[10:11], v[10:11], v[68:69], v[66:67] op_sel:[0,0,0] op_sel_hi:[0,1,1] neg_lo:[0,0,1] neg_hi:[0,0,0]
	v_pk_mul_f32 v[66:67], v[18:19], v[70:71] op_sel:[1,1] op_sel_hi:[1,0] neg_lo:[0,0] neg_hi:[0,0]
	v_pk_fma_f32 v[18:19], v[18:19], v[70:71], v[66:67] op_sel:[0,0,0] op_sel_hi:[0,1,1] neg_lo:[0,0,1] neg_hi:[0,0,0]
	v_pk_mul_f32 v[66:67], v[26:27], v[68:69] op_sel:[1,0] op_sel_hi:[1,1] neg_lo:[0,0] neg_hi:[0,0]
	v_pk_fma_f32 v[26:27], v[26:27], v[68:69], v[66:67] op_sel:[0,1,0] op_sel_hi:[0,0,1] neg_lo:[0,0,1] neg_hi:[0,0,0]
	v_pk_add_f32 v[58:59], v[2:3], v[18:19]
	v_pk_add_f32 v[60:61], v[2:3], v[18:19] neg_lo:[0,1] neg_hi:[0,1]
	v_pk_add_f32 v[62:63], v[10:11], v[26:27]
	v_pk_add_f32 v[64:65], v[10:11], v[26:27] neg_lo:[0,1] neg_hi:[0,1]
	v_pk_add_f32 v[2:3], v[58:59], v[62:63]
	v_pk_add_f32 v[18:19], v[58:59], v[62:63] neg_lo:[0,1] neg_hi:[0,1]
	v_pk_add_f32 v[10:11], v[60:61], v[64:65] op_sel:[0,1] op_sel_hi:[1,0] neg_lo:[0,1]
	v_pk_add_f32 v[26:27], v[60:61], v[64:65] op_sel:[0,1] op_sel_hi:[1,0] neg_hi:[0,1]
	v_pk_mul_f32 v[66:67], v[12:13], v[70:71] op_sel:[1,1] op_sel_hi:[1,0] neg_lo:[0,0] neg_hi:[0,0]
	v_pk_fma_f32 v[12:13], v[12:13], v[70:71], v[66:67] op_sel:[0,0,0] op_sel_hi:[0,1,1] neg_lo:[0,0,1] neg_hi:[0,0,0]
	v_pk_add_f32 v[20:21], v[20:21], 0 op_sel:[1,0] op_sel_hi:[0,0] neg_lo:[1,0]
	v_pk_mul_f32 v[66:67], v[28:29], v[70:71] op_sel:[1,1] op_sel_hi:[1,0] neg_lo:[0,0] neg_hi:[0,1]
	v_pk_fma_f32 v[28:29], v[28:29], v[70:71], v[66:67] op_sel:[0,0,0] op_sel_hi:[0,1,1] neg_lo:[0,1,1] neg_hi:[0,0,0]
	v_pk_add_f32 v[58:59], v[4:5], v[20:21]
	v_pk_add_f32 v[60:61], v[4:5], v[20:21] neg_lo:[0,1] neg_hi:[0,1]
	v_pk_add_f32 v[62:63], v[12:13], v[28:29]
	v_pk_add_f32 v[64:65], v[12:13], v[28:29] neg_lo:[0,1] neg_hi:[0,1]
	v_pk_add_f32 v[4:5], v[58:59], v[62:63]
	v_pk_add_f32 v[20:21], v[58:59], v[62:63] neg_lo:[0,1] neg_hi:[0,1]
	v_pk_add_f32 v[12:13], v[60:61], v[64:65] op_sel:[0,1] op_sel_hi:[1,0] neg_lo:[0,1]
	v_pk_add_f32 v[28:29], v[60:61], v[64:65] op_sel:[0,1] op_sel_hi:[1,0] neg_hi:[0,1]
	v_pk_mul_f32 v[66:67], v[14:15], v[68:69] op_sel:[1,0] op_sel_hi:[1,1] neg_lo:[0,0] neg_hi:[0,0]
; HD float2 cmul(float2 a, float2 b){ return make_float2(a.x*b.x - a.y*b.y, a.x*b.y + a.y*b.x); }
; HD float2 cmulc(float2 a, float2 b){ return make_float2(a.x*b.x + a.y*b.y, a.y*b.x - a.x*b.y); }
; template<bool INV, bool NOTW>
; HD void bf4c(float2* Z, int i0, int i1, int i2, int i3, float2 w1, float2 w2, float2 w3){
;   float2 a0=Z[i0], a1=Z[i1], a2=Z[i2], a3=Z[i3];
;   if (INV && !NOTW){ a1=cmulc(a1,w1); a2=cmulc(a2,w2); a3=cmulc(a3,w3); }
;   float2 s02=make_float2(a0.x+a2.x,a0.y+a2.y), d02=make_float2(a0.x-a2.x,a0.y-a2.y);
;   float2 s13=make_float2(a1.x+a3.x,a1.y+a3.y), d13=make_float2(a1.x-a3.x,a1.y-a3.y);
;   float2 y0=make_float2(s02.x+s13.x,s02.y+s13.y), y2=make_float2(s02.x-s13.x,s02.y-s13.y);
;   float2 ym=make_float2(d02.x+d13.y,d02.y-d13.x);
;   float2 yp=make_float2(d02.x-d13.y,d02.y+d13.x);
;   float2 y1, y3;
;   if (INV){ y1=yp; y3=ym; } else if (NOTW){ y1=ym; y3=yp; } else { y1=cmul(ym,w1); y2=cmul(y2,w2); y3=cmul(yp,w3); }
;   Z[i0]=y0; Z[i1]=y1; Z[i2]=y2; Z[i3]=y3;
; }
; template<bool INV, int LQ, bool BARRIER=true>
; HD void fft_pass(float2* Z, const float2* twA, const float2* twB, int tid){
;     ...
;     int j=tid&(q-1); int base0=((tid>>LQ)<<(LQ+2))+j;
;     float2 w1=make_float2(1.f,0.f), w2=w1, w3=w1;
;     if (LQ>0){ int k=j*tws; w1=cmul(twA[k>>6],twB[k&63]); w2=cmul(w1,w1); w3=cmul(w2,w1); }
;     _Pragma("unroll") for (int i=0;i<8;++i){ int base=base0+i*2048; bf4c<INV,(LQ==0)>(Z,base,base+q,base+2*q,base+3*q,w1,w2,w3); }
	v_pk_fma_f32 v[14:15], v[14:15], v[68:69], v[66:67] op_sel:[0,1,0] op_sel_hi:[0,0,1] neg_lo:[0,0,1] neg_hi:[0,0,0]
	v_pk_mul_f32 v[66:67], v[22:23], v[70:71] op_sel:[1,1] op_sel_hi:[1,0] neg_lo:[0,0] neg_hi:[0,1]
	v_pk_fma_f32 v[22:23], v[22:23], v[70:71], v[66:67] op_sel:[0,0,0] op_sel_hi:[0,1,1] neg_lo:[0,1,1] neg_hi:[0,0,0]
	v_pk_mul_f32 v[66:67], v[30:31], v[68:69] op_sel:[1,1] op_sel_hi:[1,0] neg_lo:[0,1] neg_hi:[0,1]
	v_pk_fma_f32 v[30:31], v[30:31], v[68:69], v[66:67] op_sel:[0,0,0] op_sel_hi:[0,1,1] neg_lo:[0,1,1] neg_hi:[0,1,0]
	v_pk_add_f32 v[58:59], v[6:7], v[22:23]
	v_pk_add_f32 v[60:61], v[6:7], v[22:23] neg_lo:[0,1] neg_hi:[0,1]
	v_pk_add_f32 v[62:63], v[14:15], v[30:31]
	v_pk_add_f32 v[64:65], v[14:15], v[30:31] neg_lo:[0,1] neg_hi:[0,1]
	v_pk_add_f32 v[6:7], v[58:59], v[62:63]
	v_pk_add_f32 v[22:23], v[58:59], v[62:63] neg_lo:[0,1] neg_hi:[0,1]
	v_pk_add_f32 v[14:15], v[60:61], v[64:65] op_sel:[0,1] op_sel_hi:[1,0] neg_lo:[0,1]
	v_pk_add_f32 v[30:31], v[60:61], v[64:65] op_sel:[0,1] op_sel_hi:[1,0] neg_hi:[0,1]
	s_mov_b64 exec, s[98:99]
	v_swap_b32 v0, v4
	v_swap_b32 v1, v5
	v_swap_b32 v2, v6
	v_swap_b32 v3, v7
	v_swap_b32 v8, v12
	v_swap_b32 v9, v13
	v_swap_b32 v10, v14
	v_swap_b32 v11, v15
	v_swap_b32 v16, v20
	v_swap_b32 v17, v21
	v_swap_b32 v18, v22
	v_swap_b32 v19, v23
	v_swap_b32 v24, v28
	v_swap_b32 v25, v29
	v_swap_b32 v26, v30
	v_swap_b32 v27, v31
	s_mov_b64 exec, -1
	ds_write_b128 v74, v[0:3] offset:0
	ds_write_b128 v75, v[4:7] offset:16
	ds_write_b128 v80, v[8:11] offset:32
	ds_write_b128 v81, v[12:15] offset:48
	ds_write_b128 v74, v[16:19] offset:64
	ds_write_b128 v75, v[20:23] offset:80
	ds_write_b128 v80, v[24:27] offset:96
	ds_write_b128 v81, v[28:31] offset:112
	v_add_u32_e32 v74, v223, v225
	v_sub_u32_e32 v75, v223, v225
	v_add_u32_e32 v80, v223, v225
	v_sub_u32_e32 v81, v223, v225
	ds_read_b128 v[0:3], v74 offset:0
	ds_read_b128 v[4:7], v75 offset:16
	ds_read_b128 v[8:11], v80 offset:32
	ds_read_b128 v[12:15], v81 offset:48
	ds_read_b128 v[16:19], v74 offset:64
	ds_read_b128 v[20:23], v75 offset:80
	ds_read_b128 v[24:27], v80 offset:96
	ds_read_b128 v[28:31], v81 offset:112
	s_waitcnt lgkmcnt(0)
	s_mov_b64 exec, s[98:99]
	v_swap_b32 v0, v4
	v_swap_b32 v1, v5
	v_swap_b32 v2, v6
	v_swap_b32 v3, v7
	v_swap_b32 v8, v12
	v_swap_b32 v9, v13
	v_swap_b32 v10, v14
	v_swap_b32 v11, v15
	v_swap_b32 v16, v20
	v_swap_b32 v17, v21
	v_swap_b32 v18, v22
	v_swap_b32 v19, v23
	v_swap_b32 v24, v28
	v_swap_b32 v25, v29
	v_swap_b32 v26, v30
	v_swap_b32 v27, v31
	s_mov_b64 exec, -1
	v_pk_add_f32 v[58:59], v[0:1], v[16:17]
	v_pk_add_f32 v[60:61], v[0:1], v[16:17] neg_lo:[0,1] neg_hi:[0,1]
	v_pk_add_f32 v[62:63], v[8:9], v[24:25]
	v_pk_add_f32 v[64:65], v[8:9], v[24:25] neg_lo:[0,1] neg_hi:[0,1]
	v_pk_add_f32 v[0:1], v[58:59], v[62:63]
	v_pk_add_f32 v[16:17], v[58:59], v[62:63] neg_lo:[0,1] neg_hi:[0,1]
	v_pk_add_f32 v[8:9], v[60:61], v[64:65] op_sel:[0,1] op_sel_hi:[1,0] neg_hi:[0,1]
	v_pk_add_f32 v[24:25], v[60:61], v[64:65] op_sel:[0,1] op_sel_hi:[1,0] neg_lo:[0,1]
	v_pk_add_f32 v[58:59], v[2:3], v[18:19]
	v_pk_add_f32 v[60:61], v[2:3], v[18:19] neg_lo:[0,1] neg_hi:[0,1]
	v_pk_add_f32 v[62:63], v[10:11], v[26:27]
	v_pk_add_f32 v[64:65], v[10:11], v[26:27] neg_lo:[0,1] neg_hi:[0,1]
	v_pk_add_f32 v[2:3], v[58:59], v[62:63]
	v_pk_add_f32 v[18:19], v[58:59], v[62:63] neg_lo:[0,1] neg_hi:[0,1]
	v_pk_add_f32 v[10:11], v[60:61], v[64:65] op_sel:[0,1] op_sel_hi:[1,0] neg_hi:[0,1]
	v_pk_add_f32 v[26:27], v[60:61], v[64:65] op_sel:[0,1] op_sel_hi:[1,0] neg_lo:[0,1]
	v_pk_mul_f32 v[66:67], v[10:11], v[68:69] op_sel:[1,1] op_sel_hi:[1,0] neg_lo:[0,1] neg_hi:[0,0]
	v_pk_fma_f32 v[10:11], v[10:11], v[68:69], v[66:67] op_sel:[0,0,0] op_sel_hi:[0,1,1] neg_lo:[0,0,1] neg_hi:[0,1,0]
	v_pk_mul_f32 v[66:67], v[18:19], v[70:71] op_sel:[1,1] op_sel_hi:[1,0] neg_lo:[0,1] neg_hi:[0,0]
	v_pk_fma_f32 v[18:19], v[18:19], v[70:71], v[66:67] op_sel:[0,0,0] op_sel_hi:[0,1,1] neg_lo:[0,0,1] neg_hi:[0,1,0]
	v_pk_mul_f32 v[66:67], v[26:27], v[68:69] op_sel:[1,0] op_sel_hi:[1,1] neg_lo:[0,1] neg_hi:[0,0]
	v_pk_fma_f32 v[26:27], v[26:27], v[68:69], v[66:67] op_sel:[0,1,0] op_sel_hi:[0,0,1] neg_lo:[0,0,1] neg_hi:[0,1,0]
	v_pk_add_f32 v[58:59], v[4:5], v[20:21]
	v_pk_add_f32 v[60:61], v[4:5], v[20:21] neg_lo:[0,1] neg_hi:[0,1]
	v_pk_add_f32 v[62:63], v[12:13], v[28:29]
	v_pk_add_f32 v[64:65], v[12:13], v[28:29] neg_lo:[0,1] neg_hi:[0,1]
	v_pk_add_f32 v[4:5], v[58:59], v[62:63]
	v_pk_add_f32 v[20:21], v[58:59], v[62:63] neg_lo:[0,1] neg_hi:[0,1]
	v_pk_add_f32 v[12:13], v[60:61], v[64:65] op_sel:[0,1] op_sel_hi:[1,0] neg_hi:[0,1]
	v_pk_add_f32 v[28:29], v[60:61], v[64:65] op_sel:[0,1] op_sel_hi:[1,0] neg_lo:[0,1]
	v_pk_mul_f32 v[66:67], v[12:13], v[70:71] op_sel:[1,1] op_sel_hi:[1,0] neg_lo:[0,1] neg_hi:[0,0]
	v_pk_fma_f32 v[12:13], v[12:13], v[70:71], v[66:67] op_sel:[0,0,0] op_sel_hi:[0,1,1] neg_lo:[0,0,1] neg_hi:[0,1,0]
	v_pk_add_f32 v[20:21], v[20:21], 0 op_sel:[1,0] op_sel_hi:[0,0] neg_hi:[1,0]
	v_pk_mul_f32 v[66:67], v[28:29], v[70:71] op_sel:[1,1] op_sel_hi:[1,0] neg_lo:[0,1] neg_hi:[0,1]
	v_pk_fma_f32 v[28:29], v[28:29], v[70:71], v[66:67] op_sel:[0,0,0] op_sel_hi:[0,1,1] neg_lo:[0,1,1] neg_hi:[0,1,0]
	v_pk_add_f32 v[58:59], v[6:7], v[22:23]
	v_pk_add_f32 v[60:61], v[6:7], v[22:23] neg_lo:[0,1] neg_hi:[0,1]
	v_pk_add_f32 v[62:63], v[14:15], v[30:31]
	v_pk_add_f32 v[64:65], v[14:15], v[30:31] neg_lo:[0,1] neg_hi:[0,1]
	v_pk_add_f32 v[6:7], v[58:59], v[62:63]
	v_pk_add_f32 v[22:23], v[58:59], v[62:63] neg_lo:[0,1] neg_hi:[0,1]
	v_pk_add_f32 v[14:15], v[60:61], v[64:65] op_sel:[0,1] op_sel_hi:[1,0] neg_hi:[0,1]
	v_pk_add_f32 v[30:31], v[60:61], v[64:65] op_sel:[0,1] op_sel_hi:[1,0] neg_lo:[0,1]
; HD float2 cmul(float2 a, float2 b){ return make_float2(a.x*b.x - a.y*b.y, a.x*b.y + a.y*b.x); }
; __device__ __forceinline__ void fft_mid(float2* Z, const f16x2* Hp, int tid){
;   _Pragma("unroll 4") for (int i=0;i<8;++i){ int base=(tid<<2)+i*2048;
;     u32x4 hw=*(const u32x4*)(Hp+base);
;     unsigned hw0=hw[0], hw1=hw[1], hw2=hw[2], hw3=hw[3];
;     float2 a0=Z[base], a1=Z[base+1], a2=Z[base+2], a3=Z[base+3];
;     float2 s02=make_float2(a0.x+a2.x,a0.y+a2.y), d02=make_float2(a0.x-a2.x,a0.y-a2.y);
;     float2 s13=make_float2(a1.x+a3.x,a1.y+a3.y), d13=make_float2(a1.x-a3.x,a1.y-a3.y);
;     float2 y0=make_float2(s02.x+s13.x,s02.y+s13.y), y2=make_float2(s02.x-s13.x,s02.y-s13.y);
;     float2 y1=make_float2(d02.x+d13.y,d02.y-d13.x);
;     float2 y3=make_float2(d02.x-d13.y,d02.y+d13.x);
;     f16x2 h0=__builtin_bit_cast(f16x2,hw0), h1=__builtin_bit_cast(f16x2,hw1), h2=__builtin_bit_cast(f16x2,hw2), h3=__builtin_bit_cast(f16x2,hw3);
;     float2 b0=cmul(y0,make_float2((float)h0[0],(float)h0[1])), b1=cmul(y1,make_float2((float)h1[0],(float)h1[1]));
;     float2 b2=cmul(y2,make_float2((float)h2[0],(float)h2[1])), b3=cmul(y3,make_float2((float)h3[0],(float)h3[1]));
	v_pk_mul_f32 v[66:67], v[14:15], v[68:69] op_sel:[1,0] op_sel_hi:[1,1] neg_lo:[0,1] neg_hi:[0,0]
	v_pk_fma_f32 v[14:15], v[14:15], v[68:69], v[66:67] op_sel:[0,1,0] op_sel_hi:[0,0,1] neg_lo:[0,0,1] neg_hi:[0,1,0]
	v_pk_mul_f32 v[66:67], v[22:23], v[70:71] op_sel:[1,1] op_sel_hi:[1,0] neg_lo:[0,1] neg_hi:[0,1]
	v_pk_fma_f32 v[22:23], v[22:23], v[70:71], v[66:67] op_sel:[0,0,0] op_sel_hi:[0,1,1] neg_lo:[0,1,1] neg_hi:[0,1,0]
	v_pk_mul_f32 v[66:67], v[30:31], v[68:69] op_sel:[1,1] op_sel_hi:[1,0] neg_lo:[0,0] neg_hi:[0,1]
	v_pk_fma_f32 v[30:31], v[30:31], v[68:69], v[66:67] op_sel:[0,0,0] op_sel_hi:[0,1,1] neg_lo:[0,1,1] neg_hi:[0,0,0]
	v_pk_add_f32 v[58:59], v[0:1], v[4:5]
	v_pk_add_f32 v[60:61], v[0:1], v[4:5] neg_lo:[0,1] neg_hi:[0,1]
	v_pk_add_f32 v[62:63], v[2:3], v[6:7]
	v_pk_add_f32 v[64:65], v[2:3], v[6:7] neg_lo:[0,1] neg_hi:[0,1]
	v_pk_add_f32 v[0:1], v[58:59], v[62:63]
	v_pk_add_f32 v[4:5], v[58:59], v[62:63] neg_lo:[0,1] neg_hi:[0,1]
	v_pk_add_f32 v[2:3], v[60:61], v[64:65] op_sel:[0,1] op_sel_hi:[1,0] neg_hi:[0,1]
	v_pk_add_f32 v[6:7], v[60:61], v[64:65] op_sel:[0,1] op_sel_hi:[1,0] neg_lo:[0,1]
	v_pk_add_f32 v[58:59], v[8:9], v[12:13]
	v_pk_add_f32 v[60:61], v[8:9], v[12:13] neg_lo:[0,1] neg_hi:[0,1]
	v_pk_add_f32 v[62:63], v[10:11], v[14:15]
	v_pk_add_f32 v[64:65], v[10:11], v[14:15] neg_lo:[0,1] neg_hi:[0,1]
	v_pk_add_f32 v[8:9], v[58:59], v[62:63]
	v_pk_add_f32 v[12:13], v[58:59], v[62:63] neg_lo:[0,1] neg_hi:[0,1]
	v_pk_add_f32 v[10:11], v[60:61], v[64:65] op_sel:[0,1] op_sel_hi:[1,0] neg_hi:[0,1]
	v_pk_add_f32 v[14:15], v[60:61], v[64:65] op_sel:[0,1] op_sel_hi:[1,0] neg_lo:[0,1]
	v_pk_add_f32 v[58:59], v[16:17], v[20:21]
	v_pk_add_f32 v[60:61], v[16:17], v[20:21] neg_lo:[0,1] neg_hi:[0,1]
	v_pk_add_f32 v[62:63], v[18:19], v[22:23]
	v_pk_add_f32 v[64:65], v[18:19], v[22:23] neg_lo:[0,1] neg_hi:[0,1]
	v_pk_add_f32 v[16:17], v[58:59], v[62:63]
	v_pk_add_f32 v[20:21], v[58:59], v[62:63] neg_lo:[0,1] neg_hi:[0,1]
	v_pk_add_f32 v[18:19], v[60:61], v[64:65] op_sel:[0,1] op_sel_hi:[1,0] neg_hi:[0,1]
	v_pk_add_f32 v[22:23], v[60:61], v[64:65] op_sel:[0,1] op_sel_hi:[1,0] neg_lo:[0,1]
	v_pk_add_f32 v[58:59], v[24:25], v[28:29]
	v_pk_add_f32 v[60:61], v[24:25], v[28:29] neg_lo:[0,1] neg_hi:[0,1]
	v_pk_add_f32 v[62:63], v[26:27], v[30:31]
	v_pk_add_f32 v[64:65], v[26:27], v[30:31] neg_lo:[0,1] neg_hi:[0,1]
	v_pk_add_f32 v[24:25], v[58:59], v[62:63]
	v_pk_add_f32 v[28:29], v[58:59], v[62:63] neg_lo:[0,1] neg_hi:[0,1]
	v_pk_add_f32 v[26:27], v[60:61], v[64:65] op_sel:[0,1] op_sel_hi:[1,0] neg_hi:[0,1]
	v_pk_add_f32 v[30:31], v[60:61], v[64:65] op_sel:[0,1] op_sel_hi:[1,0] neg_lo:[0,1]
	s_waitcnt vmcnt(0)
	v_cvt_f32_f16_e32 v72, v150
	v_cvt_f32_f16_sdwa v73, v150 dst_sel:DWORD dst_unused:UNUSED_PAD src0_sel:WORD_1
	s_nop 0
	v_pk_mul_f32 v[66:67], v[0:1], v[72:73] op_sel:[1,1] op_sel_hi:[1,0]
	v_pk_fma_f32 v[0:1], v[0:1], v[72:73], v[66:67] op_sel:[0,0,0] op_sel_hi:[0,1,1] neg_lo:[0,0,1]
	v_cvt_f32_f16_e32 v72, v151
	v_cvt_f32_f16_sdwa v73, v151 dst_sel:DWORD dst_unused:UNUSED_PAD src0_sel:WORD_1
	s_nop 0
	v_pk_mul_f32 v[66:67], v[2:3], v[72:73] op_sel:[1,1] op_sel_hi:[1,0]
	v_pk_fma_f32 v[2:3], v[2:3], v[72:73], v[66:67] op_sel:[0,0,0] op_sel_hi:[0,1,1] neg_lo:[0,0,1]
	v_cvt_f32_f16_e32 v72, v152
	v_cvt_f32_f16_sdwa v73, v152 dst_sel:DWORD dst_unused:UNUSED_PAD src0_sel:WORD_1
	s_nop 0
	v_pk_mul_f32 v[66:67], v[4:5], v[72:73] op_sel:[1,1] op_sel_hi:[1,0]
	v_pk_fma_f32 v[4:5], v[4:5], v[72:73], v[66:67] op_sel:[0,0,0] op_sel_hi:[0,1,1] neg_lo:[0,0,1]
	v_cvt_f32_f16_e32 v72, v153
	v_cvt_f32_f16_sdwa v73, v153 dst_sel:DWORD dst_unused:UNUSED_PAD src0_sel:WORD_1
	s_nop 0
	v_pk_mul_f32 v[66:67], v[6:7], v[72:73] op_sel:[1,1] op_sel_hi:[1,0]
	v_pk_fma_f32 v[6:7], v[6:7], v[72:73], v[66:67] op_sel:[0,0,0] op_sel_hi:[0,1,1] neg_lo:[0,0,1]
	v_cvt_f32_f16_e32 v72, v156
	v_cvt_f32_f16_sdwa v73, v156 dst_sel:DWORD dst_unused:UNUSED_PAD src0_sel:WORD_1
	s_nop 0
	v_pk_mul_f32 v[66:67], v[8:9], v[72:73] op_sel:[1,1] op_sel_hi:[1,0]
	v_pk_fma_f32 v[8:9], v[8:9], v[72:73], v[66:67] op_sel:[0,0,0] op_sel_hi:[0,1,1] neg_lo:[0,0,1]
	v_cvt_f32_f16_e32 v72, v157
	v_cvt_f32_f16_sdwa v73, v157 dst_sel:DWORD dst_unused:UNUSED_PAD src0_sel:WORD_1
	s_nop 0
	v_pk_mul_f32 v[66:67], v[10:11], v[72:73] op_sel:[1,1] op_sel_hi:[1,0]
	v_pk_fma_f32 v[10:11], v[10:11], v[72:73], v[66:67] op_sel:[0,0,0] op_sel_hi:[0,1,1] neg_lo:[0,0,1]
	v_cvt_f32_f16_e32 v72, v158
	v_cvt_f32_f16_sdwa v73, v158 dst_sel:DWORD dst_unused:UNUSED_PAD src0_sel:WORD_1
	s_nop 0
	v_pk_mul_f32 v[66:67], v[12:13], v[72:73] op_sel:[1,1] op_sel_hi:[1,0]
	v_pk_fma_f32 v[12:13], v[12:13], v[72:73], v[66:67] op_sel:[0,0,0] op_sel_hi:[0,1,1] neg_lo:[0,0,1]
	v_cvt_f32_f16_e32 v72, v159
	v_cvt_f32_f16_sdwa v73, v159 dst_sel:DWORD dst_unused:UNUSED_PAD src0_sel:WORD_1
	s_nop 0
	v_pk_mul_f32 v[66:67], v[14:15], v[72:73] op_sel:[1,1] op_sel_hi:[1,0]
	v_pk_fma_f32 v[14:15], v[14:15], v[72:73], v[66:67] op_sel:[0,0,0] op_sel_hi:[0,1,1] neg_lo:[0,0,1]
	v_cvt_f32_f16_e32 v72, v160
	v_cvt_f32_f16_sdwa v73, v160 dst_sel:DWORD dst_unused:UNUSED_PAD src0_sel:WORD_1
	s_nop 0
	v_pk_mul_f32 v[66:67], v[16:17], v[72:73] op_sel:[1,1] op_sel_hi:[1,0]
	v_pk_fma_f32 v[16:17], v[16:17], v[72:73], v[66:67] op_sel:[0,0,0] op_sel_hi:[0,1,1] neg_lo:[0,0,1]
	v_cvt_f32_f16_e32 v72, v161
	v_cvt_f32_f16_sdwa v73, v161 dst_sel:DWORD dst_unused:UNUSED_PAD src0_sel:WORD_1
	s_nop 0
	v_pk_mul_f32 v[66:67], v[18:19], v[72:73] op_sel:[1,1] op_sel_hi:[1,0]
	v_pk_fma_f32 v[18:19], v[18:19], v[72:73], v[66:67] op_sel:[0,0,0] op_sel_hi:[0,1,1] neg_lo:[0,0,1]
	v_cvt_f32_f16_e32 v72, v162
	v_cvt_f32_f16_sdwa v73, v162 dst_sel:DWORD dst_unused:UNUSED_PAD src0_sel:WORD_1
; HD float2 cmul(float2 a, float2 b){ return make_float2(a.x*b.x - a.y*b.y, a.x*b.y + a.y*b.x); }
; __device__ __forceinline__ void fft_mid(float2* Z, const f16x2* Hp, int tid){
;     ...
;     f16x2 h0=__builtin_bit_cast(f16x2,hw0), h1=__builtin_bit_cast(f16x2,hw1), h2=__builtin_bit_cast(f16x2,hw2), h3=__builtin_bit_cast(f16x2,hw3);
;     float2 b0=cmul(y0,make_float2((float)h0[0],(float)h0[1])), b1=cmul(y1,make_float2((float)h1[0],(float)h1[1]));
;     float2 b2=cmul(y2,make_float2((float)h2[0],(float)h2[1])), b3=cmul(y3,make_float2((float)h3[0],(float)h3[1]));
;     float2 t02=make_float2(b0.x+b2.x,b0.y+b2.y), e02=make_float2(b0.x-b2.x,b0.y-b2.y);
;     float2 t13=make_float2(b1.x+b3.x,b1.y+b3.y), e13=make_float2(b1.x-b3.x,b1.y-b3.y);
;     Z[base]=make_float2(t02.x+t13.x,t02.y+t13.y); Z[base+2]=make_float2(t02.x-t13.x,t02.y-t13.y);
;     Z[base+1]=make_float2(e02.x-e13.y,e02.y+e13.x);
;     Z[base+3]=make_float2(e02.x+e13.y,e02.y-e13.x);
	s_nop 0
	v_pk_mul_f32 v[66:67], v[20:21], v[72:73] op_sel:[1,1] op_sel_hi:[1,0]
	v_pk_fma_f32 v[20:21], v[20:21], v[72:73], v[66:67] op_sel:[0,0,0] op_sel_hi:[0,1,1] neg_lo:[0,0,1]
	v_cvt_f32_f16_e32 v72, v163
	v_cvt_f32_f16_sdwa v73, v163 dst_sel:DWORD dst_unused:UNUSED_PAD src0_sel:WORD_1
	s_nop 0
	v_pk_mul_f32 v[66:67], v[22:23], v[72:73] op_sel:[1,1] op_sel_hi:[1,0]
	v_pk_fma_f32 v[22:23], v[22:23], v[72:73], v[66:67] op_sel:[0,0,0] op_sel_hi:[0,1,1] neg_lo:[0,0,1]
	v_cvt_f32_f16_e32 v72, v164
	v_cvt_f32_f16_sdwa v73, v164 dst_sel:DWORD dst_unused:UNUSED_PAD src0_sel:WORD_1
	s_nop 0
	v_pk_mul_f32 v[66:67], v[24:25], v[72:73] op_sel:[1,1] op_sel_hi:[1,0]
	v_pk_fma_f32 v[24:25], v[24:25], v[72:73], v[66:67] op_sel:[0,0,0] op_sel_hi:[0,1,1] neg_lo:[0,0,1]
	v_cvt_f32_f16_e32 v72, v165
	v_cvt_f32_f16_sdwa v73, v165 dst_sel:DWORD dst_unused:UNUSED_PAD src0_sel:WORD_1
	s_nop 0
	v_pk_mul_f32 v[66:67], v[26:27], v[72:73] op_sel:[1,1] op_sel_hi:[1,0]
	v_pk_fma_f32 v[26:27], v[26:27], v[72:73], v[66:67] op_sel:[0,0,0] op_sel_hi:[0,1,1] neg_lo:[0,0,1]
	v_cvt_f32_f16_e32 v72, v166
	v_cvt_f32_f16_sdwa v73, v166 dst_sel:DWORD dst_unused:UNUSED_PAD src0_sel:WORD_1
	s_nop 0
	v_pk_mul_f32 v[66:67], v[28:29], v[72:73] op_sel:[1,1] op_sel_hi:[1,0]
	v_pk_fma_f32 v[28:29], v[28:29], v[72:73], v[66:67] op_sel:[0,0,0] op_sel_hi:[0,1,1] neg_lo:[0,0,1]
	v_cvt_f32_f16_e32 v72, v167
	v_cvt_f32_f16_sdwa v73, v167 dst_sel:DWORD dst_unused:UNUSED_PAD src0_sel:WORD_1
	s_nop 0
	v_pk_mul_f32 v[66:67], v[30:31], v[72:73] op_sel:[1,1] op_sel_hi:[1,0]
	v_pk_fma_f32 v[30:31], v[30:31], v[72:73], v[66:67] op_sel:[0,0,0] op_sel_hi:[0,1,1] neg_lo:[0,0,1]
	v_pk_add_f32 v[58:59], v[0:1], v[4:5]
	v_pk_add_f32 v[60:61], v[0:1], v[4:5] neg_lo:[0,1] neg_hi:[0,1]
	v_pk_add_f32 v[62:63], v[2:3], v[6:7]
	v_pk_add_f32 v[64:65], v[2:3], v[6:7] neg_lo:[0,1] neg_hi:[0,1]
	v_pk_add_f32 v[0:1], v[58:59], v[62:63]
	v_pk_add_f32 v[4:5], v[58:59], v[62:63] neg_lo:[0,1] neg_hi:[0,1]
	v_pk_add_f32 v[2:3], v[60:61], v[64:65] op_sel:[0,1] op_sel_hi:[1,0] neg_lo:[0,1]
	v_pk_add_f32 v[6:7], v[60:61], v[64:65] op_sel:[0,1] op_sel_hi:[1,0] neg_hi:[0,1]
	v_pk_add_f32 v[58:59], v[8:9], v[12:13]
	v_pk_add_f32 v[60:61], v[8:9], v[12:13] neg_lo:[0,1] neg_hi:[0,1]
	v_pk_add_f32 v[62:63], v[10:11], v[14:15]
	v_pk_add_f32 v[64:65], v[10:11], v[14:15] neg_lo:[0,1] neg_hi:[0,1]
	v_pk_add_f32 v[8:9], v[58:59], v[62:63]
	v_pk_add_f32 v[12:13], v[58:59], v[62:63] neg_lo:[0,1] neg_hi:[0,1]
	v_pk_add_f32 v[10:11], v[60:61], v[64:65] op_sel:[0,1] op_sel_hi:[1,0] neg_lo:[0,1]
	v_pk_add_f32 v[14:15], v[60:61], v[64:65] op_sel:[0,1] op_sel_hi:[1,0] neg_hi:[0,1]
	v_pk_add_f32 v[58:59], v[16:17], v[20:21]
	v_pk_add_f32 v[60:61], v[16:17], v[20:21] neg_lo:[0,1] neg_hi:[0,1]
	v_pk_add_f32 v[62:63], v[18:19], v[22:23]
	v_pk_add_f32 v[64:65], v[18:19], v[22:23] neg_lo:[0,1] neg_hi:[0,1]
	v_pk_add_f32 v[16:17], v[58:59], v[62:63]
	v_pk_add_f32 v[20:21], v[58:59], v[62:63] neg_lo:[0,1] neg_hi:[0,1]
	v_pk_add_f32 v[18:19], v[60:61], v[64:65] op_sel:[0,1] op_sel_hi:[1,0] neg_lo:[0,1]
	v_pk_add_f32 v[22:23], v[60:61], v[64:65] op_sel:[0,1] op_sel_hi:[1,0] neg_hi:[0,1]
	v_pk_add_f32 v[58:59], v[24:25], v[28:29]
	v_pk_add_f32 v[60:61], v[24:25], v[28:29] neg_lo:[0,1] neg_hi:[0,1]
	v_pk_add_f32 v[62:63], v[26:27], v[30:31]
	v_pk_add_f32 v[64:65], v[26:27], v[30:31] neg_lo:[0,1] neg_hi:[0,1]
	v_pk_add_f32 v[24:25], v[58:59], v[62:63]
	v_pk_add_f32 v[28:29], v[58:59], v[62:63] neg_lo:[0,1] neg_hi:[0,1]
	v_pk_add_f32 v[26:27], v[60:61], v[64:65] op_sel:[0,1] op_sel_hi:[1,0] neg_lo:[0,1]
	v_pk_add_f32 v[30:31], v[60:61], v[64:65] op_sel:[0,1] op_sel_hi:[1,0] neg_hi:[0,1]
	v_pk_add_f32 v[58:59], v[0:1], v[16:17]
	v_pk_add_f32 v[60:61], v[0:1], v[16:17] neg_lo:[0,1] neg_hi:[0,1]
	v_pk_add_f32 v[62:63], v[8:9], v[24:25]
	v_pk_add_f32 v[64:65], v[8:9], v[24:25] neg_lo:[0,1] neg_hi:[0,1]
	v_pk_add_f32 v[0:1], v[58:59], v[62:63]
	v_pk_add_f32 v[16:17], v[58:59], v[62:63] neg_lo:[0,1] neg_hi:[0,1]
	v_pk_add_f32 v[8:9], v[60:61], v[64:65] op_sel:[0,1] op_sel_hi:[1,0] neg_lo:[0,1]
	v_pk_add_f32 v[24:25], v[60:61], v[64:65] op_sel:[0,1] op_sel_hi:[1,0] neg_hi:[0,1]
	v_pk_mul_f32 v[66:67], v[10:11], v[68:69] op_sel:[1,1] op_sel_hi:[1,0] neg_lo:[0,0] neg_hi:[0,0]
; HD float2 cmul(float2 a, float2 b){ return make_float2(a.x*b.x - a.y*b.y, a.x*b.y + a.y*b.x); }
; HD float2 cmulc(float2 a, float2 b){ return make_float2(a.x*b.x + a.y*b.y, a.y*b.x - a.x*b.y); }
; template<bool INV, bool NOTW>
; HD void bf4c(float2* Z, int i0, int i1, int i2, int i3, float2 w1, float2 w2, float2 w3){
;   float2 a0=Z[i0], a1=Z[i1], a2=Z[i2], a3=Z[i3];
;   if (INV && !NOTW){ a1=cmulc(a1,w1); a2=cmulc(a2,w2); a3=cmulc(a3,w3); }
;   float2 s02=make_float2(a0.x+a2.x,a0.y+a2.y), d02=make_float2(a0.x-a2.x,a0.y-a2.y);
;   float2 s13=make_float2(a1.x+a3.x,a1.y+a3.y), d13=make_float2(a1.x-a3.x,a1.y-a3.y);
;   float2 y0=make_float2(s02.x+s13.x,s02.y+s13.y), y2=make_float2(s02.x-s13.x,s02.y-s13.y);
;   float2 ym=make_float2(d02.x+d13.y,d02.y-d13.x);
;   float2 yp=make_float2(d02.x-d13.y,d02.y+d13.x);
;   float2 y1, y3;
;   if (INV){ y1=yp; y3=ym; } else if (NOTW){ y1=ym; y3=yp; } else { y1=cmul(ym,w1); y2=cmul(y2,w2); y3=cmul(yp,w3); }
;   Z[i0]=y0; Z[i1]=y1; Z[i2]=y2; Z[i3]=y3;
; }
; template<bool INV, int LQ, bool BARRIER=true>
; HD void fft_pass(float2* Z, const float2* twA, const float2* twB, int tid){
;     ...
;     int j=tid&(q-1); int base0=((tid>>LQ)<<(LQ+2))+j;
;     float2 w1=make_float2(1.f,0.f), w2=w1, w3=w1;
;     if (LQ>0){ int k=j*tws; w1=cmul(twA[k>>6],twB[k&63]); w2=cmul(w1,w1); w3=cmul(w2,w1); }
;     _Pragma("unroll") for (int i=0;i<8;++i){ int base=base0+i*2048; bf4c<INV,(LQ==0)>(Z,base,base+q,base+2*q,base+3*q,w1,w2,w3); }
;   }
;   if (BARRIER) __syncthreads(); else asm volatile("s_waitcnt lgkmcnt(0)" ::: "memory");
	v_pk_fma_f32 v[10:11], v[10:11], v[68:69], v[66:67] op_sel:[0,0,0] op_sel_hi:[0,1,1] neg_lo:[0,0,1] neg_hi:[0,0,0]
	v_pk_mul_f32 v[66:67], v[18:19], v[70:71] op_sel:[1,1] op_sel_hi:[1,0] neg_lo:[0,0] neg_hi:[0,0]
	v_pk_fma_f32 v[18:19], v[18:19], v[70:71], v[66:67] op_sel:[0,0,0] op_sel_hi:[0,1,1] neg_lo:[0,0,1] neg_hi:[0,0,0]
	v_pk_mul_f32 v[66:67], v[26:27], v[68:69] op_sel:[1,0] op_sel_hi:[1,1] neg_lo:[0,0] neg_hi:[0,0]
	v_pk_fma_f32 v[26:27], v[26:27], v[68:69], v[66:67] op_sel:[0,1,0] op_sel_hi:[0,0,1] neg_lo:[0,0,1] neg_hi:[0,0,0]
	v_pk_add_f32 v[58:59], v[2:3], v[18:19]
	v_pk_add_f32 v[60:61], v[2:3], v[18:19] neg_lo:[0,1] neg_hi:[0,1]
	v_pk_add_f32 v[62:63], v[10:11], v[26:27]
	v_pk_add_f32 v[64:65], v[10:11], v[26:27] neg_lo:[0,1] neg_hi:[0,1]
	v_pk_add_f32 v[2:3], v[58:59], v[62:63]
	v_pk_add_f32 v[18:19], v[58:59], v[62:63] neg_lo:[0,1] neg_hi:[0,1]
	v_pk_add_f32 v[10:11], v[60:61], v[64:65] op_sel:[0,1] op_sel_hi:[1,0] neg_lo:[0,1]
	v_pk_add_f32 v[26:27], v[60:61], v[64:65] op_sel:[0,1] op_sel_hi:[1,0] neg_hi:[0,1]
	v_pk_mul_f32 v[66:67], v[12:13], v[70:71] op_sel:[1,1] op_sel_hi:[1,0] neg_lo:[0,0] neg_hi:[0,0]
	v_pk_fma_f32 v[12:13], v[12:13], v[70:71], v[66:67] op_sel:[0,0,0] op_sel_hi:[0,1,1] neg_lo:[0,0,1] neg_hi:[0,0,0]
	v_pk_add_f32 v[20:21], v[20:21], 0 op_sel:[1,0] op_sel_hi:[0,0] neg_lo:[1,0]
	v_pk_mul_f32 v[66:67], v[28:29], v[70:71] op_sel:[1,1] op_sel_hi:[1,0] neg_lo:[0,0] neg_hi:[0,1]
	v_pk_fma_f32 v[28:29], v[28:29], v[70:71], v[66:67] op_sel:[0,0,0] op_sel_hi:[0,1,1] neg_lo:[0,1,1] neg_hi:[0,0,0]
	v_pk_add_f32 v[58:59], v[4:5], v[20:21]
	v_pk_add_f32 v[60:61], v[4:5], v[20:21] neg_lo:[0,1] neg_hi:[0,1]
	v_pk_add_f32 v[62:63], v[12:13], v[28:29]
	v_pk_add_f32 v[64:65], v[12:13], v[28:29] neg_lo:[0,1] neg_hi:[0,1]
	v_pk_add_f32 v[4:5], v[58:59], v[62:63]
	v_pk_add_f32 v[20:21], v[58:59], v[62:63] neg_lo:[0,1] neg_hi:[0,1]
	v_pk_add_f32 v[12:13], v[60:61], v[64:65] op_sel:[0,1] op_sel_hi:[1,0] neg_lo:[0,1]
	v_pk_add_f32 v[28:29], v[60:61], v[64:65] op_sel:[0,1] op_sel_hi:[1,0] neg_hi:[0,1]
	v_pk_mul_f32 v[66:67], v[14:15], v[68:69] op_sel:[1,0] op_sel_hi:[1,1] neg_lo:[0,0] neg_hi:[0,0]
	v_pk_fma_f32 v[14:15], v[14:15], v[68:69], v[66:67] op_sel:[0,1,0] op_sel_hi:[0,0,1] neg_lo:[0,0,1] neg_hi:[0,0,0]
	v_pk_mul_f32 v[66:67], v[22:23], v[70:71] op_sel:[1,1] op_sel_hi:[1,0] neg_lo:[0,0] neg_hi:[0,1]
	v_pk_fma_f32 v[22:23], v[22:23], v[70:71], v[66:67] op_sel:[0,0,0] op_sel_hi:[0,1,1] neg_lo:[0,1,1] neg_hi:[0,0,0]
	v_pk_mul_f32 v[66:67], v[30:31], v[68:69] op_sel:[1,1] op_sel_hi:[1,0] neg_lo:[0,1] neg_hi:[0,1]
	v_pk_fma_f32 v[30:31], v[30:31], v[68:69], v[66:67] op_sel:[0,0,0] op_sel_hi:[0,1,1] neg_lo:[0,1,1] neg_hi:[0,1,0]
	v_pk_add_f32 v[58:59], v[6:7], v[22:23]
	v_pk_add_f32 v[60:61], v[6:7], v[22:23] neg_lo:[0,1] neg_hi:[0,1]
	v_pk_add_f32 v[62:63], v[14:15], v[30:31]
	v_pk_add_f32 v[64:65], v[14:15], v[30:31] neg_lo:[0,1] neg_hi:[0,1]
	v_pk_add_f32 v[6:7], v[58:59], v[62:63]
	v_pk_add_f32 v[22:23], v[58:59], v[62:63] neg_lo:[0,1] neg_hi:[0,1]
	v_pk_add_f32 v[14:15], v[60:61], v[64:65] op_sel:[0,1] op_sel_hi:[1,0] neg_lo:[0,1]
	v_pk_add_f32 v[30:31], v[60:61], v[64:65] op_sel:[0,1] op_sel_hi:[1,0] neg_hi:[0,1]
	s_mov_b64 exec, s[98:99]
	v_swap_b32 v0, v4
	v_swap_b32 v1, v5
	v_swap_b32 v2, v6
	v_swap_b32 v3, v7
	v_swap_b32 v8, v12
	v_swap_b32 v9, v13
	v_swap_b32 v10, v14
	v_swap_b32 v11, v15
	v_swap_b32 v16, v20
	v_swap_b32 v17, v21
	v_swap_b32 v18, v22
	v_swap_b32 v19, v23
	v_swap_b32 v24, v28
	v_swap_b32 v25, v29
	v_swap_b32 v26, v30
	v_swap_b32 v27, v31
	s_mov_b64 exec, -1
	ds_write_b128 v74, v[0:3] offset:0
	ds_write_b128 v75, v[4:7] offset:16
	ds_write_b128 v80, v[8:11] offset:32
	ds_write_b128 v81, v[12:15] offset:48
	ds_write_b128 v74, v[16:19] offset:64
	ds_write_b128 v75, v[20:23] offset:80
	ds_write_b128 v80, v[24:27] offset:96
	ds_write_b128 v81, v[28:31] offset:112
	s_waitcnt lgkmcnt(0)
	s_mov_b64 s[18:19], 0x8000
	v_lshlrev_b32_e32 v232, 4, v154
	s_lshl_b32 s100, s90, 15
	v_add_u32_e32 v233, 0x2000, v232
	v_add_u32_e32 v234, 0x4000, v232
	v_add_u32_e32 v235, 0x6000, v232
	s_add_u32 s98, s70, 0x42bd000
	s_addc_u32 s99, s71, 0
	s_add_u32 s98, s98, s100
	s_addc_u32 s99, s99, 0
	s_cmp_eq_u32 s89, 1
	s_cbranch_scc1 .Lmy_pf_st1
	s_add_u32 s98, s98, 0x2000000
	s_addc_u32 s99, s99, 0

; HD float2 cmul(float2 a, float2 b){ return make_float2(a.x*b.x - a.y*b.y, a.x*b.y + a.y*b.x); }
; HD float2 cmulc(float2 a, float2 b){ return make_float2(a.x*b.x + a.y*b.y, a.y*b.x - a.x*b.y); }
; HD void inv12_half(const float2* Z, const float2* twA, const float2* twB, int t, float2& x0, float2& x1){
;   float2 w1=cmul(twA[t>>6],twB[t&63]), w2=cmul(w1,w1), w3=cmul(w2,w1);
;   float2 b0=Z[t], b1=cmulc(Z[t+4096],w1), b2=cmulc(Z[t+8192],w2), b3=cmulc(Z[t+12288],w3);
;   float2 s02=make_float2(b0.x+b2.x,b0.y+b2.y), d02=make_float2(b0.x-b2.x,b0.y-b2.y);
;   float2 s13=make_float2(b1.x+b3.x,b1.y+b3.y), d13=make_float2(b1.x-b3.x,b1.y-b3.y);
;   x0=make_float2(s02.x+s13.x,s02.y+s13.y);
;   x1=make_float2(d02.x-d13.y,d02.y+d13.x);
; }
; __device__ __forceinline__ void phase_hyena(KP kp_, int hf){ asm volatile("" : "+s"(kp_)); const Params p=load_params(kp_);
;     ...
;         if (st==1){ int tq=tid; asm volatile("" : "+v"(tq));
;           _Pragma("unroll 4") for (int i=0;i<8;++i){ int tb=tq+512*i; float2 xr[2]; inv12_half(Z,twA,twB,tb,xr[0],xr[1]);
;             _Pragma("unroll") for (int hh=0;hh<2;++hh){ int t=tb+hh*4096;
;               float u0=hconv3(rv,t,wv0,wv1,wv2,bv_), u1=hconv3(rv+8192,t,wv0,wv1,wv2,bv_);
;               float x0=hconv3(r1,t,wa0,wa1,wa2,ba_), x1=hconv3(r1+8192,t,wa0,wa1,wa2,ba_);
;               float2 y=xr[hh]; y.x*=(1.f/16384.f); y.y*=(1.f/16384.f);
;               Zs[t]=make_float2(x0*(y.x+u0*bias0), x1*(y.y+u1*bias0)); } }
.LBB0_1340:
	s_and_b64 vcc, exec, s[12:13]
	s_cbranch_vccz .LBB0_1343
	v_lshlrev_b32_e32 v6, 1, v86
	v_add_u32_e32 v142, 0x1000000, v6
	v_add_u32_e32 v143, 0x1001000, v6
	v_add_u32_e32 v144, 0x1002000, v6
	v_add_u32_e32 v145, 0x1003000, v6
	v_add_u32_e32 v150, 0x1004000, v6
	v_add_u32_e32 v151, 0x1005000, v6
	v_add_u32_e32 v152, 0x1006000, v6
	v_add_u32_e32 v153, 0x1007000, v6
	v_lshlrev_b32_e32 v5, 3, v86
	v_mov_b32_e32 v8, v5
	v_add_u32_e32 v9, 0x10000, v5
	v_lshrrev_b32_e32 v7, 6, v86
	v_lshl_add_u32 v7, v7, 3, s88
	v_and_b32_e32 v6, 63, v86
	v_lshl_add_u32 v6, v6, 3, s91
	ds_read_b64 v[10:11], v6
	s_sub_u32 s12, s96, 0x2000000
	s_subb_u32 s13, s97, 0
	global_load_ushort v230, v142, s[12:13] offset:0
	global_load_ushort v231, v150, s[12:13] offset:0
	global_load_ushort v234, v144, s[12:13] offset:0
	global_load_ushort v235, v152, s[12:13] offset:0
	ds_read_b64 v[12:13], v7 offset:0
	ds_read_b64 v[14:15], v8 offset:0
	ds_read_b64 v[16:17], v8 offset:32768
	ds_read_b64 v[18:19], v9 offset:0
	ds_read_b64 v[20:21], v9 offset:32768
	global_load_ushort v242, v142, s[12:13] offset:1024
	global_load_ushort v243, v150, s[12:13] offset:1024
	global_load_ushort v246, v144, s[12:13] offset:1024
	global_load_ushort v247, v152, s[12:13] offset:1024
	ds_read_b64 v[58:59], v7 offset:64
	ds_read_b64 v[60:61], v8 offset:4096
	ds_read_b64 v[62:63], v8 offset:36864
	ds_read_b64 v[64:65], v9 offset:4096
	ds_read_b64 v[66:67], v9 offset:36864
	s_waitcnt lgkmcnt(5)
	v_pk_mul_f32 v[222:223], v[12:13], v[10:11] op_sel:[1,1] op_sel_hi:[1,0]
	v_pk_fma_f32 v[22:23], v[12:13], v[10:11], v[222:223] op_sel:[0,0,0] op_sel_hi:[0,1,1] neg_lo:[0,0,1]
	v_pk_mul_f32 v[222:223], v[22:23], v[22:23] op_sel:[1,1] op_sel_hi:[1,0]
	v_pk_fma_f32 v[24:25], v[22:23], v[22:23], v[222:223] op_sel:[0,0,0] op_sel_hi:[0,1,1] neg_lo:[0,0,1]
	v_pk_mul_f32 v[222:223], v[24:25], v[22:23] op_sel:[1,1] op_sel_hi:[1,0]
	v_pk_fma_f32 v[26:27], v[24:25], v[22:23], v[222:223] op_sel:[0,0,0] op_sel_hi:[0,1,1] neg_lo:[0,0,1]
	v_pk_mul_f32 v[222:223], v[16:17], v[22:23] op_sel:[1,1] op_sel_hi:[0,1]
	v_pk_fma_f32 v[28:29], v[16:17], v[22:23], v[222:223] op_sel:[0,0,0] op_sel_hi:[1,0,1] neg_hi:[0,0,1]
	v_pk_mul_f32 v[222:223], v[18:19], v[24:25] op_sel:[1,1] op_sel_hi:[0,1]
	v_pk_fma_f32 v[30:31], v[18:19], v[24:25], v[222:223] op_sel:[0,0,0] op_sel_hi:[1,0,1] neg_hi:[0,0,1]
	v_pk_mul_f32 v[222:223], v[20:21], v[26:27] op_sel:[1,1] op_sel_hi:[0,1]
	v_pk_fma_f32 v[68:69], v[20:21], v[26:27], v[222:223] op_sel:[0,0,0] op_sel_hi:[1,0,1] neg_hi:[0,0,1]
	v_pk_add_f32 v[70:71], v[14:15], v[30:31]
	v_pk_add_f32 v[72:73], v[14:15], v[30:31] neg_lo:[0,1] neg_hi:[0,1]
	v_pk_add_f32 v[74:75], v[28:29], v[68:69]
	v_pk_add_f32 v[80:81], v[28:29], v[68:69] neg_lo:[0,1] neg_hi:[0,1]
	v_pk_add_f32 v[82:83], v[70:71], v[74:75]
	v_pk_add_f32 v[84:85], v[72:73], v[80:81] op_sel:[0,1] op_sel_hi:[1,0] neg_lo:[0,1]
	s_waitcnt vmcnt(4)
	v_lshlrev_b32_e32 v224, 16, v104
	v_lshlrev_b32_e32 v225, 16, v105
	v_mov_b32_e32 v226, 0
	v_mov_b32_e32 v227, 0
	v_mov_b32_e32 v170, 0
	v_mov_b32_e32 v171, 0
	v_mov_b32_dpp v226, v224 wave_shr:1 row_mask:0xf bank_mask:0xf
	v_mov_b32_dpp v227, v225 wave_shr:1 row_mask:0xf bank_mask:0xf
	v_mov_b32_dpp v170, v224 wave_shl:1 row_mask:0xf bank_mask:0xf
	v_mov_b32_dpp v171, v225 wave_shl:1 row_mask:0xf bank_mask:0xf
	v_pk_mul_f32 v[172:173], v[34:35], v[224:225]
	v_pk_fma_f32 v[172:173], v[32:33], v[226:227], v[172:173]
	v_pk_fma_f32 v[172:173], v[36:37], v[170:171], v[172:173]
	v_pk_add_f32 v[174:175], v[38:39], v[172:173]
	v_lshlrev_b32_e32 v224, 16, v230
	v_lshlrev_b32_e32 v225, 16, v231
	v_mov_b32_e32 v226, 0
	v_mov_b32_e32 v227, 0
	v_mov_b32_e32 v170, 0
	v_mov_b32_e32 v171, 0
	v_mov_b32_dpp v226, v224 wave_shr:1 row_mask:0xf bank_mask:0xf
	v_mov_b32_dpp v227, v225 wave_shr:1 row_mask:0xf bank_mask:0xf
	v_mov_b32_dpp v170, v224 wave_shl:1 row_mask:0xf bank_mask:0xf
	v_mov_b32_dpp v171, v225 wave_shl:1 row_mask:0xf bank_mask:0xf
	v_pk_mul_f32 v[172:173], v[42:43], v[224:225]
	v_pk_fma_f32 v[172:173], v[40:41], v[226:227], v[172:173]
	v_pk_fma_f32 v[172:173], v[44:45], v[170:171], v[172:173]
	v_pk_add_f32 v[156:157], v[46:47], v[172:173]
	v_lshlrev_b32_e32 v224, 16, v106
	v_lshlrev_b32_e32 v225, 16, v107
	v_mov_b32_e32 v226, 0
	v_mov_b32_e32 v227, 0
	v_mov_b32_e32 v170, 0
	v_mov_b32_e32 v171, 0
	v_mov_b32_dpp v226, v224 wave_shr:1 row_mask:0xf bank_mask:0xf
	v_mov_b32_dpp v227, v225 wave_shr:1 row_mask:0xf bank_mask:0xf
	v_mov_b32_dpp v170, v224 wave_shl:1 row_mask:0xf bank_mask:0xf
	v_mov_b32_dpp v171, v225 wave_shl:1 row_mask:0xf bank_mask:0xf
	v_pk_mul_f32 v[172:173], v[34:35], v[224:225]
	v_pk_fma_f32 v[172:173], v[32:33], v[226:227], v[172:173]
	v_pk_fma_f32 v[172:173], v[36:37], v[170:171], v[172:173]
	v_pk_add_f32 v[176:177], v[38:39], v[172:173]
	v_lshlrev_b32_e32 v224, 16, v234
	v_lshlrev_b32_e32 v225, 16, v235
	v_mov_b32_e32 v226, 0
	v_mov_b32_e32 v227, 0
	v_mov_b32_e32 v170, 0
	v_mov_b32_e32 v171, 0
	v_mov_b32_dpp v226, v224 wave_shr:1 row_mask:0xf bank_mask:0xf
	v_mov_b32_dpp v227, v225 wave_shr:1 row_mask:0xf bank_mask:0xf
	v_mov_b32_dpp v170, v224 wave_shl:1 row_mask:0xf bank_mask:0xf
	v_mov_b32_dpp v171, v225 wave_shl:1 row_mask:0xf bank_mask:0xf
	v_pk_mul_f32 v[172:173], v[42:43], v[224:225]
	v_pk_fma_f32 v[172:173], v[40:41], v[226:227], v[172:173]
	v_pk_fma_f32 v[172:173], v[44:45], v[170:171], v[172:173]
	v_pk_add_f32 v[158:159], v[46:47], v[172:173]
	v_pk_mul_f32 v[174:175], v[48:49], v[174:175]
	v_pk_fma_f32 v[82:83], v[82:83], s[66:67], v[174:175] op_sel_hi:[1,0,1]
	v_pk_mul_f32 v[82:83], v[82:83], v[156:157]
	v_add_u32_e32 v6, 0x0, v5
	global_store_dwordx2 v6, v[82:83], s[80:81]
	v_pk_mul_f32 v[176:177], v[48:49], v[176:177]
	v_pk_fma_f32 v[84:85], v[84:85], s[66:67], v[176:177] op_sel_hi:[1,0,1]
	v_pk_mul_f32 v[84:85], v[84:85], v[158:159]
	v_add_u32_e32 v6, 0x8000, v5
	global_store_dwordx2 v6, v[84:85], s[80:81]
	global_load_ushort v230, v142, s[12:13] offset:2048
	global_load_ushort v231, v150, s[12:13] offset:2048
	global_load_ushort v234, v144, s[12:13] offset:2048
	global_load_ushort v235, v152, s[12:13] offset:2048
	ds_read_b64 v[12:13], v7 offset:128
	ds_read_b64 v[14:15], v8 offset:8192
	ds_read_b64 v[16:17], v8 offset:40960
	ds_read_b64 v[18:19], v9 offset:8192
	ds_read_b64 v[20:21], v9 offset:40960
	s_waitcnt lgkmcnt(5)
; HD float2 cmul(float2 a, float2 b){ return make_float2(a.x*b.x - a.y*b.y, a.x*b.y + a.y*b.x); }
; HD float2 cmulc(float2 a, float2 b){ return make_float2(a.x*b.x + a.y*b.y, a.y*b.x - a.x*b.y); }
; HD void inv12_half(const float2* Z, const float2* twA, const float2* twB, int t, float2& x0, float2& x1){
;   float2 w1=cmul(twA[t>>6],twB[t&63]), w2=cmul(w1,w1), w3=cmul(w2,w1);
;   float2 b0=Z[t], b1=cmulc(Z[t+4096],w1), b2=cmulc(Z[t+8192],w2), b3=cmulc(Z[t+12288],w3);
;   float2 s02=make_float2(b0.x+b2.x,b0.y+b2.y), d02=make_float2(b0.x-b2.x,b0.y-b2.y);
;   float2 s13=make_float2(b1.x+b3.x,b1.y+b3.y), d13=make_float2(b1.x-b3.x,b1.y-b3.y);
;   x0=make_float2(s02.x+s13.x,s02.y+s13.y);
;   x1=make_float2(d02.x-d13.y,d02.y+d13.x);
; }
; __device__ __forceinline__ void phase_hyena(KP kp_, int hf){ asm volatile("" : "+s"(kp_)); const Params p=load_params(kp_);
;     ...
;         if (st==1){ int tq=tid; asm volatile("" : "+v"(tq));
;           _Pragma("unroll 4") for (int i=0;i<8;++i){ int tb=tq+512*i; float2 xr[2]; inv12_half(Z,twA,twB,tb,xr[0],xr[1]);
;             _Pragma("unroll") for (int hh=0;hh<2;++hh){ int t=tb+hh*4096;
;               float u0=hconv3(rv,t,wv0,wv1,wv2,bv_), u1=hconv3(rv+8192,t,wv0,wv1,wv2,bv_);
;               float x0=hconv3(r1,t,wa0,wa1,wa2,ba_), x1=hconv3(r1+8192,t,wa0,wa1,wa2,ba_);
;               float2 y=xr[hh]; y.x*=(1.f/16384.f); y.y*=(1.f/16384.f);
;               Zs[t]=make_float2(x0*(y.x+u0*bias0), x1*(y.y+u1*bias0)); } }
	v_pk_mul_f32 v[222:223], v[58:59], v[10:11] op_sel:[1,1] op_sel_hi:[1,0]
	v_pk_fma_f32 v[22:23], v[58:59], v[10:11], v[222:223] op_sel:[0,0,0] op_sel_hi:[0,1,1] neg_lo:[0,0,1]
	v_pk_mul_f32 v[222:223], v[22:23], v[22:23] op_sel:[1,1] op_sel_hi:[1,0]
	v_pk_fma_f32 v[24:25], v[22:23], v[22:23], v[222:223] op_sel:[0,0,0] op_sel_hi:[0,1,1] neg_lo:[0,0,1]
	v_pk_mul_f32 v[222:223], v[24:25], v[22:23] op_sel:[1,1] op_sel_hi:[1,0]
	v_pk_fma_f32 v[26:27], v[24:25], v[22:23], v[222:223] op_sel:[0,0,0] op_sel_hi:[0,1,1] neg_lo:[0,0,1]
	v_pk_mul_f32 v[222:223], v[62:63], v[22:23] op_sel:[1,1] op_sel_hi:[0,1]
	v_pk_fma_f32 v[28:29], v[62:63], v[22:23], v[222:223] op_sel:[0,0,0] op_sel_hi:[1,0,1] neg_hi:[0,0,1]
	v_pk_mul_f32 v[222:223], v[64:65], v[24:25] op_sel:[1,1] op_sel_hi:[0,1]
	v_pk_fma_f32 v[30:31], v[64:65], v[24:25], v[222:223] op_sel:[0,0,0] op_sel_hi:[1,0,1] neg_hi:[0,0,1]
	v_pk_mul_f32 v[222:223], v[66:67], v[26:27] op_sel:[1,1] op_sel_hi:[0,1]
	v_pk_fma_f32 v[68:69], v[66:67], v[26:27], v[222:223] op_sel:[0,0,0] op_sel_hi:[1,0,1] neg_hi:[0,0,1]
	v_pk_add_f32 v[70:71], v[60:61], v[30:31]
	v_pk_add_f32 v[72:73], v[60:61], v[30:31] neg_lo:[0,1] neg_hi:[0,1]
	v_pk_add_f32 v[74:75], v[28:29], v[68:69]
	v_pk_add_f32 v[80:81], v[28:29], v[68:69] neg_lo:[0,1] neg_hi:[0,1]
	v_pk_add_f32 v[82:83], v[70:71], v[74:75]
	v_pk_add_f32 v[84:85], v[72:73], v[80:81] op_sel:[0,1] op_sel_hi:[1,0] neg_lo:[0,1]
	s_waitcnt vmcnt(6)
	v_lshlrev_b32_e32 v224, 16, v108
	v_lshlrev_b32_e32 v225, 16, v109
	v_mov_b32_e32 v226, 0
	v_mov_b32_e32 v227, 0
	v_mov_b32_e32 v170, 0
	v_mov_b32_e32 v171, 0
	v_mov_b32_dpp v226, v224 wave_shr:1 row_mask:0xf bank_mask:0xf
	v_mov_b32_dpp v227, v225 wave_shr:1 row_mask:0xf bank_mask:0xf
	v_mov_b32_dpp v170, v224 wave_shl:1 row_mask:0xf bank_mask:0xf
	v_mov_b32_dpp v171, v225 wave_shl:1 row_mask:0xf bank_mask:0xf
	v_pk_mul_f32 v[172:173], v[34:35], v[224:225]
	v_pk_fma_f32 v[172:173], v[32:33], v[226:227], v[172:173]
	v_pk_fma_f32 v[172:173], v[36:37], v[170:171], v[172:173]
	v_pk_add_f32 v[174:175], v[38:39], v[172:173]
	v_lshlrev_b32_e32 v224, 16, v242
	v_lshlrev_b32_e32 v225, 16, v243
	v_mov_b32_e32 v226, 0
	v_mov_b32_e32 v227, 0
	v_mov_b32_e32 v170, 0
	v_mov_b32_e32 v171, 0
	v_mov_b32_dpp v226, v224 wave_shr:1 row_mask:0xf bank_mask:0xf
	v_mov_b32_dpp v227, v225 wave_shr:1 row_mask:0xf bank_mask:0xf
	v_mov_b32_dpp v170, v224 wave_shl:1 row_mask:0xf bank_mask:0xf
	v_mov_b32_dpp v171, v225 wave_shl:1 row_mask:0xf bank_mask:0xf
	v_pk_mul_f32 v[172:173], v[42:43], v[224:225]
	v_pk_fma_f32 v[172:173], v[40:41], v[226:227], v[172:173]
	v_pk_fma_f32 v[172:173], v[44:45], v[170:171], v[172:173]
	v_pk_add_f32 v[156:157], v[46:47], v[172:173]
	v_lshlrev_b32_e32 v224, 16, v110
	v_lshlrev_b32_e32 v225, 16, v111
	v_mov_b32_e32 v226, 0
	v_mov_b32_e32 v227, 0
	v_mov_b32_e32 v170, 0
	v_mov_b32_e32 v171, 0
	v_mov_b32_dpp v226, v224 wave_shr:1 row_mask:0xf bank_mask:0xf
	v_mov_b32_dpp v227, v225 wave_shr:1 row_mask:0xf bank_mask:0xf
	v_mov_b32_dpp v170, v224 wave_shl:1 row_mask:0xf bank_mask:0xf
	v_mov_b32_dpp v171, v225 wave_shl:1 row_mask:0xf bank_mask:0xf
	v_pk_mul_f32 v[172:173], v[34:35], v[224:225]
	v_pk_fma_f32 v[172:173], v[32:33], v[226:227], v[172:173]
	v_pk_fma_f32 v[172:173], v[36:37], v[170:171], v[172:173]
	v_pk_add_f32 v[176:177], v[38:39], v[172:173]
	v_lshlrev_b32_e32 v224, 16, v246
	v_lshlrev_b32_e32 v225, 16, v247
	v_mov_b32_e32 v226, 0
	v_mov_b32_e32 v227, 0
	v_mov_b32_e32 v170, 0
	v_mov_b32_e32 v171, 0
	v_mov_b32_dpp v226, v224 wave_shr:1 row_mask:0xf bank_mask:0xf
	v_mov_b32_dpp v227, v225 wave_shr:1 row_mask:0xf bank_mask:0xf
	v_mov_b32_dpp v170, v224 wave_shl:1 row_mask:0xf bank_mask:0xf
	v_mov_b32_dpp v171, v225 wave_shl:1 row_mask:0xf bank_mask:0xf
	v_pk_mul_f32 v[172:173], v[42:43], v[224:225]
	v_pk_fma_f32 v[172:173], v[40:41], v[226:227], v[172:173]
	v_pk_fma_f32 v[172:173], v[44:45], v[170:171], v[172:173]
	v_pk_add_f32 v[158:159], v[46:47], v[172:173]
	v_pk_mul_f32 v[174:175], v[48:49], v[174:175]
	v_pk_fma_f32 v[82:83], v[82:83], s[66:67], v[174:175] op_sel_hi:[1,0,1]
	v_pk_mul_f32 v[82:83], v[82:83], v[156:157]
	v_add_u32_e32 v6, 0x1000, v5
	global_store_dwordx2 v6, v[82:83], s[80:81]
	v_pk_mul_f32 v[176:177], v[48:49], v[176:177]
	v_pk_fma_f32 v[84:85], v[84:85], s[66:67], v[176:177] op_sel_hi:[1,0,1]
	v_pk_mul_f32 v[84:85], v[84:85], v[158:159]
	v_add_u32_e32 v6, 0x9000, v5
	global_store_dwordx2 v6, v[84:85], s[80:81]
	global_load_ushort v242, v142, s[12:13] offset:3072
	global_load_ushort v243, v150, s[12:13] offset:3072
	global_load_ushort v246, v144, s[12:13] offset:3072
	global_load_ushort v247, v152, s[12:13] offset:3072
	ds_read_b64 v[58:59], v7 offset:192
	ds_read_b64 v[60:61], v8 offset:12288
	ds_read_b64 v[62:63], v8 offset:45056
	ds_read_b64 v[64:65], v9 offset:12288
	ds_read_b64 v[66:67], v9 offset:45056
	s_waitcnt lgkmcnt(5)
	v_pk_mul_f32 v[222:223], v[12:13], v[10:11] op_sel:[1,1] op_sel_hi:[1,0]
	v_pk_fma_f32 v[22:23], v[12:13], v[10:11], v[222:223] op_sel:[0,0,0] op_sel_hi:[0,1,1] neg_lo:[0,0,1]
	v_pk_mul_f32 v[222:223], v[22:23], v[22:23] op_sel:[1,1] op_sel_hi:[1,0]
	v_pk_fma_f32 v[24:25], v[22:23], v[22:23], v[222:223] op_sel:[0,0,0] op_sel_hi:[0,1,1] neg_lo:[0,0,1]
	v_pk_mul_f32 v[222:223], v[24:25], v[22:23] op_sel:[1,1] op_sel_hi:[1,0]
	v_pk_fma_f32 v[26:27], v[24:25], v[22:23], v[222:223] op_sel:[0,0,0] op_sel_hi:[0,1,1] neg_lo:[0,0,1]
	v_pk_mul_f32 v[222:223], v[16:17], v[22:23] op_sel:[1,1] op_sel_hi:[0,1]
	v_pk_fma_f32 v[28:29], v[16:17], v[22:23], v[222:223] op_sel:[0,0,0] op_sel_hi:[1,0,1] neg_hi:[0,0,1]
	v_pk_mul_f32 v[222:223], v[18:19], v[24:25] op_sel:[1,1] op_sel_hi:[0,1]
	v_pk_fma_f32 v[30:31], v[18:19], v[24:25], v[222:223] op_sel:[0,0,0] op_sel_hi:[1,0,1] neg_hi:[0,0,1]
	v_pk_mul_f32 v[222:223], v[20:21], v[26:27] op_sel:[1,1] op_sel_hi:[0,1]
	v_pk_fma_f32 v[68:69], v[20:21], v[26:27], v[222:223] op_sel:[0,0,0] op_sel_hi:[1,0,1] neg_hi:[0,0,1]
	v_pk_add_f32 v[70:71], v[14:15], v[30:31]
	v_pk_add_f32 v[72:73], v[14:15], v[30:31] neg_lo:[0,1] neg_hi:[0,1]
	v_pk_add_f32 v[74:75], v[28:29], v[68:69]
	v_pk_add_f32 v[80:81], v[28:29], v[68:69] neg_lo:[0,1] neg_hi:[0,1]
	v_pk_add_f32 v[82:83], v[70:71], v[74:75]
	v_pk_add_f32 v[84:85], v[72:73], v[80:81] op_sel:[0,1] op_sel_hi:[1,0] neg_lo:[0,1]
	s_waitcnt vmcnt(6)
; HD float2 cmul(float2 a, float2 b){ return make_float2(a.x*b.x - a.y*b.y, a.x*b.y + a.y*b.x); }
; HD float2 cmulc(float2 a, float2 b){ return make_float2(a.x*b.x + a.y*b.y, a.y*b.x - a.x*b.y); }
; HD void inv12_half(const float2* Z, const float2* twA, const float2* twB, int t, float2& x0, float2& x1){
;   float2 w1=cmul(twA[t>>6],twB[t&63]), w2=cmul(w1,w1), w3=cmul(w2,w1);
;   float2 b0=Z[t], b1=cmulc(Z[t+4096],w1), b2=cmulc(Z[t+8192],w2), b3=cmulc(Z[t+12288],w3);
;   float2 s02=make_float2(b0.x+b2.x,b0.y+b2.y), d02=make_float2(b0.x-b2.x,b0.y-b2.y);
;   float2 s13=make_float2(b1.x+b3.x,b1.y+b3.y), d13=make_float2(b1.x-b3.x,b1.y-b3.y);
;   x0=make_float2(s02.x+s13.x,s02.y+s13.y);
;   x1=make_float2(d02.x-d13.y,d02.y+d13.x);
; }
; __device__ __forceinline__ void phase_hyena(KP kp_, int hf){ asm volatile("" : "+s"(kp_)); const Params p=load_params(kp_);
;     ...
;         if (st==1){ int tq=tid; asm volatile("" : "+v"(tq));
;           _Pragma("unroll 4") for (int i=0;i<8;++i){ int tb=tq+512*i; float2 xr[2]; inv12_half(Z,twA,twB,tb,xr[0],xr[1]);
;             _Pragma("unroll") for (int hh=0;hh<2;++hh){ int t=tb+hh*4096;
;               float u0=hconv3(rv,t,wv0,wv1,wv2,bv_), u1=hconv3(rv+8192,t,wv0,wv1,wv2,bv_);
;               float x0=hconv3(r1,t,wa0,wa1,wa2,ba_), x1=hconv3(r1+8192,t,wa0,wa1,wa2,ba_);
;               float2 y=xr[hh]; y.x*=(1.f/16384.f); y.y*=(1.f/16384.f);
;               Zs[t]=make_float2(x0*(y.x+u0*bias0), x1*(y.y+u1*bias0)); } }
	v_lshlrev_b32_e32 v224, 16, v112
	v_lshlrev_b32_e32 v225, 16, v113
	v_mov_b32_e32 v226, 0
	v_mov_b32_e32 v227, 0
	v_mov_b32_e32 v170, 0
	v_mov_b32_e32 v171, 0
	v_mov_b32_dpp v226, v224 wave_shr:1 row_mask:0xf bank_mask:0xf
	v_mov_b32_dpp v227, v225 wave_shr:1 row_mask:0xf bank_mask:0xf
	v_mov_b32_dpp v170, v224 wave_shl:1 row_mask:0xf bank_mask:0xf
	v_mov_b32_dpp v171, v225 wave_shl:1 row_mask:0xf bank_mask:0xf
	v_pk_mul_f32 v[172:173], v[34:35], v[224:225]
	v_pk_fma_f32 v[172:173], v[32:33], v[226:227], v[172:173]
	v_pk_fma_f32 v[172:173], v[36:37], v[170:171], v[172:173]
	v_pk_add_f32 v[174:175], v[38:39], v[172:173]
	v_lshlrev_b32_e32 v224, 16, v230
	v_lshlrev_b32_e32 v225, 16, v231
	v_mov_b32_e32 v226, 0
	v_mov_b32_e32 v227, 0
	v_mov_b32_e32 v170, 0
	v_mov_b32_e32 v171, 0
	v_mov_b32_dpp v226, v224 wave_shr:1 row_mask:0xf bank_mask:0xf
	v_mov_b32_dpp v227, v225 wave_shr:1 row_mask:0xf bank_mask:0xf
	v_mov_b32_dpp v170, v224 wave_shl:1 row_mask:0xf bank_mask:0xf
	v_mov_b32_dpp v171, v225 wave_shl:1 row_mask:0xf bank_mask:0xf
	v_pk_mul_f32 v[172:173], v[42:43], v[224:225]
	v_pk_fma_f32 v[172:173], v[40:41], v[226:227], v[172:173]
	v_pk_fma_f32 v[172:173], v[44:45], v[170:171], v[172:173]
	v_pk_add_f32 v[156:157], v[46:47], v[172:173]
	v_lshlrev_b32_e32 v224, 16, v114
	v_lshlrev_b32_e32 v225, 16, v115
	v_mov_b32_e32 v226, 0
	v_mov_b32_e32 v227, 0
	v_mov_b32_e32 v170, 0
	v_mov_b32_e32 v171, 0
	v_mov_b32_dpp v226, v224 wave_shr:1 row_mask:0xf bank_mask:0xf
	v_mov_b32_dpp v227, v225 wave_shr:1 row_mask:0xf bank_mask:0xf
	v_mov_b32_dpp v170, v224 wave_shl:1 row_mask:0xf bank_mask:0xf
	v_mov_b32_dpp v171, v225 wave_shl:1 row_mask:0xf bank_mask:0xf
	v_pk_mul_f32 v[172:173], v[34:35], v[224:225]
	v_pk_fma_f32 v[172:173], v[32:33], v[226:227], v[172:173]
	v_pk_fma_f32 v[172:173], v[36:37], v[170:171], v[172:173]
	v_pk_add_f32 v[176:177], v[38:39], v[172:173]
	v_lshlrev_b32_e32 v224, 16, v234
	v_lshlrev_b32_e32 v225, 16, v235
	v_mov_b32_e32 v226, 0
	v_mov_b32_e32 v227, 0
	v_mov_b32_e32 v170, 0
	v_mov_b32_e32 v171, 0
	v_mov_b32_dpp v226, v224 wave_shr:1 row_mask:0xf bank_mask:0xf
	v_mov_b32_dpp v227, v225 wave_shr:1 row_mask:0xf bank_mask:0xf
	v_mov_b32_dpp v170, v224 wave_shl:1 row_mask:0xf bank_mask:0xf
	v_mov_b32_dpp v171, v225 wave_shl:1 row_mask:0xf bank_mask:0xf
	v_pk_mul_f32 v[172:173], v[42:43], v[224:225]
	v_pk_fma_f32 v[172:173], v[40:41], v[226:227], v[172:173]
	v_pk_fma_f32 v[172:173], v[44:45], v[170:171], v[172:173]
	v_pk_add_f32 v[158:159], v[46:47], v[172:173]
	v_pk_mul_f32 v[174:175], v[48:49], v[174:175]
	v_pk_fma_f32 v[82:83], v[82:83], s[66:67], v[174:175] op_sel_hi:[1,0,1]
	v_pk_mul_f32 v[82:83], v[82:83], v[156:157]
	v_add_u32_e32 v6, 0x2000, v5
	global_store_dwordx2 v6, v[82:83], s[80:81]
	v_pk_mul_f32 v[176:177], v[48:49], v[176:177]
	v_pk_fma_f32 v[84:85], v[84:85], s[66:67], v[176:177] op_sel_hi:[1,0,1]
	v_pk_mul_f32 v[84:85], v[84:85], v[158:159]
	v_add_u32_e32 v6, 0xa000, v5
	global_store_dwordx2 v6, v[84:85], s[80:81]
	global_load_ushort v230, v143, s[12:13] offset:0
	global_load_ushort v231, v151, s[12:13] offset:0
	global_load_ushort v234, v145, s[12:13] offset:0
	global_load_ushort v235, v153, s[12:13] offset:0
	ds_read_b64 v[12:13], v7 offset:256
	ds_read_b64 v[14:15], v8 offset:16384
	ds_read_b64 v[16:17], v8 offset:49152
	ds_read_b64 v[18:19], v9 offset:16384
	ds_read_b64 v[20:21], v9 offset:49152
	s_waitcnt lgkmcnt(5)
	v_pk_mul_f32 v[222:223], v[58:59], v[10:11] op_sel:[1,1] op_sel_hi:[1,0]
	v_pk_fma_f32 v[22:23], v[58:59], v[10:11], v[222:223] op_sel:[0,0,0] op_sel_hi:[0,1,1] neg_lo:[0,0,1]
	v_pk_mul_f32 v[222:223], v[22:23], v[22:23] op_sel:[1,1] op_sel_hi:[1,0]
	v_pk_fma_f32 v[24:25], v[22:23], v[22:23], v[222:223] op_sel:[0,0,0] op_sel_hi:[0,1,1] neg_lo:[0,0,1]
	v_pk_mul_f32 v[222:223], v[24:25], v[22:23] op_sel:[1,1] op_sel_hi:[1,0]
	v_pk_fma_f32 v[26:27], v[24:25], v[22:23], v[222:223] op_sel:[0,0,0] op_sel_hi:[0,1,1] neg_lo:[0,0,1]
	v_pk_mul_f32 v[222:223], v[62:63], v[22:23] op_sel:[1,1] op_sel_hi:[0,1]
	v_pk_fma_f32 v[28:29], v[62:63], v[22:23], v[222:223] op_sel:[0,0,0] op_sel_hi:[1,0,1] neg_hi:[0,0,1]
	v_pk_mul_f32 v[222:223], v[64:65], v[24:25] op_sel:[1,1] op_sel_hi:[0,1]
	v_pk_fma_f32 v[30:31], v[64:65], v[24:25], v[222:223] op_sel:[0,0,0] op_sel_hi:[1,0,1] neg_hi:[0,0,1]
	v_pk_mul_f32 v[222:223], v[66:67], v[26:27] op_sel:[1,1] op_sel_hi:[0,1]
	v_pk_fma_f32 v[68:69], v[66:67], v[26:27], v[222:223] op_sel:[0,0,0] op_sel_hi:[1,0,1] neg_hi:[0,0,1]
	v_pk_add_f32 v[70:71], v[60:61], v[30:31]
	v_pk_add_f32 v[72:73], v[60:61], v[30:31] neg_lo:[0,1] neg_hi:[0,1]
	v_pk_add_f32 v[74:75], v[28:29], v[68:69]
	v_pk_add_f32 v[80:81], v[28:29], v[68:69] neg_lo:[0,1] neg_hi:[0,1]
	v_pk_add_f32 v[82:83], v[70:71], v[74:75]
	v_pk_add_f32 v[84:85], v[72:73], v[80:81] op_sel:[0,1] op_sel_hi:[1,0] neg_lo:[0,1]
	s_waitcnt vmcnt(6)
; HD float2 cmul(float2 a, float2 b){ return make_float2(a.x*b.x - a.y*b.y, a.x*b.y + a.y*b.x); }
; HD float2 cmulc(float2 a, float2 b){ return make_float2(a.x*b.x + a.y*b.y, a.y*b.x - a.x*b.y); }
; HD void inv12_half(const float2* Z, const float2* twA, const float2* twB, int t, float2& x0, float2& x1){
;   float2 w1=cmul(twA[t>>6],twB[t&63]), w2=cmul(w1,w1), w3=cmul(w2,w1);
;   float2 b0=Z[t], b1=cmulc(Z[t+4096],w1), b2=cmulc(Z[t+8192],w2), b3=cmulc(Z[t+12288],w3);
;   float2 s02=make_float2(b0.x+b2.x,b0.y+b2.y), d02=make_float2(b0.x-b2.x,b0.y-b2.y);
;   float2 s13=make_float2(b1.x+b3.x,b1.y+b3.y), d13=make_float2(b1.x-b3.x,b1.y-b3.y);
;   x0=make_float2(s02.x+s13.x,s02.y+s13.y);
;   x1=make_float2(d02.x-d13.y,d02.y+d13.x);
; }
; __device__ __forceinline__ void phase_hyena(KP kp_, int hf){ asm volatile("" : "+s"(kp_)); const Params p=load_params(kp_);
;     ...
;         if (st==1){ int tq=tid; asm volatile("" : "+v"(tq));
;           _Pragma("unroll 4") for (int i=0;i<8;++i){ int tb=tq+512*i; float2 xr[2]; inv12_half(Z,twA,twB,tb,xr[0],xr[1]);
;             _Pragma("unroll") for (int hh=0;hh<2;++hh){ int t=tb+hh*4096;
;               float u0=hconv3(rv,t,wv0,wv1,wv2,bv_), u1=hconv3(rv+8192,t,wv0,wv1,wv2,bv_);
;               float x0=hconv3(r1,t,wa0,wa1,wa2,ba_), x1=hconv3(r1+8192,t,wa0,wa1,wa2,ba_);
;               float2 y=xr[hh]; y.x*=(1.f/16384.f); y.y*=(1.f/16384.f);
;               Zs[t]=make_float2(x0*(y.x+u0*bias0), x1*(y.y+u1*bias0)); } }
	v_lshlrev_b32_e32 v224, 16, v116
	v_lshlrev_b32_e32 v225, 16, v117
	v_mov_b32_e32 v226, 0
	v_mov_b32_e32 v227, 0
	v_mov_b32_e32 v170, 0
	v_mov_b32_e32 v171, 0
	v_mov_b32_dpp v226, v224 wave_shr:1 row_mask:0xf bank_mask:0xf
	v_mov_b32_dpp v227, v225 wave_shr:1 row_mask:0xf bank_mask:0xf
	v_mov_b32_dpp v170, v224 wave_shl:1 row_mask:0xf bank_mask:0xf
	v_mov_b32_dpp v171, v225 wave_shl:1 row_mask:0xf bank_mask:0xf
	v_pk_mul_f32 v[172:173], v[34:35], v[224:225]
	v_pk_fma_f32 v[172:173], v[32:33], v[226:227], v[172:173]
	v_pk_fma_f32 v[172:173], v[36:37], v[170:171], v[172:173]
	v_pk_add_f32 v[174:175], v[38:39], v[172:173]
	v_lshlrev_b32_e32 v224, 16, v242
	v_lshlrev_b32_e32 v225, 16, v243
	v_mov_b32_e32 v226, 0
	v_mov_b32_e32 v227, 0
	v_mov_b32_e32 v170, 0
	v_mov_b32_e32 v171, 0
	v_mov_b32_dpp v226, v224 wave_shr:1 row_mask:0xf bank_mask:0xf
	v_mov_b32_dpp v227, v225 wave_shr:1 row_mask:0xf bank_mask:0xf
	v_mov_b32_dpp v170, v224 wave_shl:1 row_mask:0xf bank_mask:0xf
	v_mov_b32_dpp v171, v225 wave_shl:1 row_mask:0xf bank_mask:0xf
	v_pk_mul_f32 v[172:173], v[42:43], v[224:225]
	v_pk_fma_f32 v[172:173], v[40:41], v[226:227], v[172:173]
	v_pk_fma_f32 v[172:173], v[44:45], v[170:171], v[172:173]
	v_pk_add_f32 v[156:157], v[46:47], v[172:173]
	v_lshlrev_b32_e32 v224, 16, v118
	v_lshlrev_b32_e32 v225, 16, v119
	v_mov_b32_e32 v226, 0
	v_mov_b32_e32 v227, 0
	v_mov_b32_e32 v170, 0
	v_mov_b32_e32 v171, 0
	v_mov_b32_dpp v226, v224 wave_shr:1 row_mask:0xf bank_mask:0xf
	v_mov_b32_dpp v227, v225 wave_shr:1 row_mask:0xf bank_mask:0xf
	v_mov_b32_dpp v170, v224 wave_shl:1 row_mask:0xf bank_mask:0xf
	v_mov_b32_dpp v171, v225 wave_shl:1 row_mask:0xf bank_mask:0xf
	v_pk_mul_f32 v[172:173], v[34:35], v[224:225]
	v_pk_fma_f32 v[172:173], v[32:33], v[226:227], v[172:173]
	v_pk_fma_f32 v[172:173], v[36:37], v[170:171], v[172:173]
	v_pk_add_f32 v[176:177], v[38:39], v[172:173]
	v_lshlrev_b32_e32 v224, 16, v246
	v_lshlrev_b32_e32 v225, 16, v247
	v_mov_b32_e32 v226, 0
	v_mov_b32_e32 v227, 0
	v_mov_b32_e32 v170, 0
	v_mov_b32_e32 v171, 0
	v_mov_b32_dpp v226, v224 wave_shr:1 row_mask:0xf bank_mask:0xf
	v_mov_b32_dpp v227, v225 wave_shr:1 row_mask:0xf bank_mask:0xf
	v_mov_b32_dpp v170, v224 wave_shl:1 row_mask:0xf bank_mask:0xf
	v_mov_b32_dpp v171, v225 wave_shl:1 row_mask:0xf bank_mask:0xf
	v_pk_mul_f32 v[172:173], v[42:43], v[224:225]
	v_pk_fma_f32 v[172:173], v[40:41], v[226:227], v[172:173]
	v_pk_fma_f32 v[172:173], v[44:45], v[170:171], v[172:173]
	v_pk_add_f32 v[158:159], v[46:47], v[172:173]
	v_pk_mul_f32 v[174:175], v[48:49], v[174:175]
	v_pk_fma_f32 v[82:83], v[82:83], s[66:67], v[174:175] op_sel_hi:[1,0,1]
	v_pk_mul_f32 v[82:83], v[82:83], v[156:157]
	v_add_u32_e32 v6, 0x3000, v5
	global_store_dwordx2 v6, v[82:83], s[80:81]
	v_pk_mul_f32 v[176:177], v[48:49], v[176:177]
	v_pk_fma_f32 v[84:85], v[84:85], s[66:67], v[176:177] op_sel_hi:[1,0,1]
	v_pk_mul_f32 v[84:85], v[84:85], v[158:159]
	v_add_u32_e32 v6, 0xb000, v5
	global_store_dwordx2 v6, v[84:85], s[80:81]
	global_load_ushort v242, v143, s[12:13] offset:1024
	global_load_ushort v243, v151, s[12:13] offset:1024
	global_load_ushort v246, v145, s[12:13] offset:1024
	global_load_ushort v247, v153, s[12:13] offset:1024
	ds_read_b64 v[58:59], v7 offset:320
	ds_read_b64 v[60:61], v8 offset:20480
	ds_read_b64 v[62:63], v8 offset:53248
	ds_read_b64 v[64:65], v9 offset:20480
	ds_read_b64 v[66:67], v9 offset:53248
	s_waitcnt lgkmcnt(5)
	v_pk_mul_f32 v[222:223], v[12:13], v[10:11] op_sel:[1,1] op_sel_hi:[1,0]
	v_pk_fma_f32 v[22:23], v[12:13], v[10:11], v[222:223] op_sel:[0,0,0] op_sel_hi:[0,1,1] neg_lo:[0,0,1]
	v_pk_mul_f32 v[222:223], v[22:23], v[22:23] op_sel:[1,1] op_sel_hi:[1,0]
	v_pk_fma_f32 v[24:25], v[22:23], v[22:23], v[222:223] op_sel:[0,0,0] op_sel_hi:[0,1,1] neg_lo:[0,0,1]
	v_pk_mul_f32 v[222:223], v[24:25], v[22:23] op_sel:[1,1] op_sel_hi:[1,0]
	v_pk_fma_f32 v[26:27], v[24:25], v[22:23], v[222:223] op_sel:[0,0,0] op_sel_hi:[0,1,1] neg_lo:[0,0,1]
	v_pk_mul_f32 v[222:223], v[16:17], v[22:23] op_sel:[1,1] op_sel_hi:[0,1]
	v_pk_fma_f32 v[28:29], v[16:17], v[22:23], v[222:223] op_sel:[0,0,0] op_sel_hi:[1,0,1] neg_hi:[0,0,1]
	v_pk_mul_f32 v[222:223], v[18:19], v[24:25] op_sel:[1,1] op_sel_hi:[0,1]
	v_pk_fma_f32 v[30:31], v[18:19], v[24:25], v[222:223] op_sel:[0,0,0] op_sel_hi:[1,0,1] neg_hi:[0,0,1]
	v_pk_mul_f32 v[222:223], v[20:21], v[26:27] op_sel:[1,1] op_sel_hi:[0,1]
	v_pk_fma_f32 v[68:69], v[20:21], v[26:27], v[222:223] op_sel:[0,0,0] op_sel_hi:[1,0,1] neg_hi:[0,0,1]
	v_pk_add_f32 v[70:71], v[14:15], v[30:31]
	v_pk_add_f32 v[72:73], v[14:15], v[30:31] neg_lo:[0,1] neg_hi:[0,1]
	v_pk_add_f32 v[74:75], v[28:29], v[68:69]
	v_pk_add_f32 v[80:81], v[28:29], v[68:69] neg_lo:[0,1] neg_hi:[0,1]
	v_pk_add_f32 v[82:83], v[70:71], v[74:75]
	v_pk_add_f32 v[84:85], v[72:73], v[80:81] op_sel:[0,1] op_sel_hi:[1,0] neg_lo:[0,1]
	s_waitcnt vmcnt(6)
; HD float2 cmul(float2 a, float2 b){ return make_float2(a.x*b.x - a.y*b.y, a.x*b.y + a.y*b.x); }
; HD float2 cmulc(float2 a, float2 b){ return make_float2(a.x*b.x + a.y*b.y, a.y*b.x - a.x*b.y); }
; HD void inv12_half(const float2* Z, const float2* twA, const float2* twB, int t, float2& x0, float2& x1){
;   float2 w1=cmul(twA[t>>6],twB[t&63]), w2=cmul(w1,w1), w3=cmul(w2,w1);
;   float2 b0=Z[t], b1=cmulc(Z[t+4096],w1), b2=cmulc(Z[t+8192],w2), b3=cmulc(Z[t+12288],w3);
;   float2 s02=make_float2(b0.x+b2.x,b0.y+b2.y), d02=make_float2(b0.x-b2.x,b0.y-b2.y);
;   float2 s13=make_float2(b1.x+b3.x,b1.y+b3.y), d13=make_float2(b1.x-b3.x,b1.y-b3.y);
;   x0=make_float2(s02.x+s13.x,s02.y+s13.y);
;   x1=make_float2(d02.x-d13.y,d02.y+d13.x);
; }
; __device__ __forceinline__ void phase_hyena(KP kp_, int hf){ asm volatile("" : "+s"(kp_)); const Params p=load_params(kp_);
;     ...
;         if (st==1){ int tq=tid; asm volatile("" : "+v"(tq));
;           _Pragma("unroll 4") for (int i=0;i<8;++i){ int tb=tq+512*i; float2 xr[2]; inv12_half(Z,twA,twB,tb,xr[0],xr[1]);
;             _Pragma("unroll") for (int hh=0;hh<2;++hh){ int t=tb+hh*4096;
;               float u0=hconv3(rv,t,wv0,wv1,wv2,bv_), u1=hconv3(rv+8192,t,wv0,wv1,wv2,bv_);
;               float x0=hconv3(r1,t,wa0,wa1,wa2,ba_), x1=hconv3(r1+8192,t,wa0,wa1,wa2,ba_);
;               float2 y=xr[hh]; y.x*=(1.f/16384.f); y.y*=(1.f/16384.f);
;               Zs[t]=make_float2(x0*(y.x+u0*bias0), x1*(y.y+u1*bias0)); } }
	v_lshlrev_b32_e32 v224, 16, v120
	v_lshlrev_b32_e32 v225, 16, v121
	v_mov_b32_e32 v226, 0
	v_mov_b32_e32 v227, 0
	v_mov_b32_e32 v170, 0
	v_mov_b32_e32 v171, 0
	v_mov_b32_dpp v226, v224 wave_shr:1 row_mask:0xf bank_mask:0xf
	v_mov_b32_dpp v227, v225 wave_shr:1 row_mask:0xf bank_mask:0xf
	v_mov_b32_dpp v170, v224 wave_shl:1 row_mask:0xf bank_mask:0xf
	v_mov_b32_dpp v171, v225 wave_shl:1 row_mask:0xf bank_mask:0xf
	v_pk_mul_f32 v[172:173], v[34:35], v[224:225]
	v_pk_fma_f32 v[172:173], v[32:33], v[226:227], v[172:173]
	v_pk_fma_f32 v[172:173], v[36:37], v[170:171], v[172:173]
	v_pk_add_f32 v[174:175], v[38:39], v[172:173]
	v_lshlrev_b32_e32 v224, 16, v230
	v_lshlrev_b32_e32 v225, 16, v231
	v_mov_b32_e32 v226, 0
	v_mov_b32_e32 v227, 0
	v_mov_b32_e32 v170, 0
	v_mov_b32_e32 v171, 0
	v_mov_b32_dpp v226, v224 wave_shr:1 row_mask:0xf bank_mask:0xf
	v_mov_b32_dpp v227, v225 wave_shr:1 row_mask:0xf bank_mask:0xf
	v_mov_b32_dpp v170, v224 wave_shl:1 row_mask:0xf bank_mask:0xf
	v_mov_b32_dpp v171, v225 wave_shl:1 row_mask:0xf bank_mask:0xf
	v_pk_mul_f32 v[172:173], v[42:43], v[224:225]
	v_pk_fma_f32 v[172:173], v[40:41], v[226:227], v[172:173]
	v_pk_fma_f32 v[172:173], v[44:45], v[170:171], v[172:173]
	v_pk_add_f32 v[156:157], v[46:47], v[172:173]
	v_lshlrev_b32_e32 v224, 16, v122
	v_lshlrev_b32_e32 v225, 16, v123
	v_mov_b32_e32 v226, 0
	v_mov_b32_e32 v227, 0
	v_mov_b32_e32 v170, 0
	v_mov_b32_e32 v171, 0
	v_mov_b32_dpp v226, v224 wave_shr:1 row_mask:0xf bank_mask:0xf
	v_mov_b32_dpp v227, v225 wave_shr:1 row_mask:0xf bank_mask:0xf
	v_mov_b32_dpp v170, v224 wave_shl:1 row_mask:0xf bank_mask:0xf
	v_mov_b32_dpp v171, v225 wave_shl:1 row_mask:0xf bank_mask:0xf
	v_pk_mul_f32 v[172:173], v[34:35], v[224:225]
	v_pk_fma_f32 v[172:173], v[32:33], v[226:227], v[172:173]
	v_pk_fma_f32 v[172:173], v[36:37], v[170:171], v[172:173]
	v_pk_add_f32 v[176:177], v[38:39], v[172:173]
	v_lshlrev_b32_e32 v224, 16, v234
	v_lshlrev_b32_e32 v225, 16, v235
	v_mov_b32_e32 v226, 0
	v_mov_b32_e32 v227, 0
	v_mov_b32_e32 v170, 0
	v_mov_b32_e32 v171, 0
	v_mov_b32_dpp v226, v224 wave_shr:1 row_mask:0xf bank_mask:0xf
	v_mov_b32_dpp v227, v225 wave_shr:1 row_mask:0xf bank_mask:0xf
	v_mov_b32_dpp v170, v224 wave_shl:1 row_mask:0xf bank_mask:0xf
	v_mov_b32_dpp v171, v225 wave_shl:1 row_mask:0xf bank_mask:0xf
	v_pk_mul_f32 v[172:173], v[42:43], v[224:225]
	v_pk_fma_f32 v[172:173], v[40:41], v[226:227], v[172:173]
	v_pk_fma_f32 v[172:173], v[44:45], v[170:171], v[172:173]
	v_pk_add_f32 v[158:159], v[46:47], v[172:173]
	v_pk_mul_f32 v[174:175], v[48:49], v[174:175]
	v_pk_fma_f32 v[82:83], v[82:83], s[66:67], v[174:175] op_sel_hi:[1,0,1]
	v_pk_mul_f32 v[82:83], v[82:83], v[156:157]
	v_add_u32_e32 v6, 0x4000, v5
	global_store_dwordx2 v6, v[82:83], s[80:81]
	v_pk_mul_f32 v[176:177], v[48:49], v[176:177]
	v_pk_fma_f32 v[84:85], v[84:85], s[66:67], v[176:177] op_sel_hi:[1,0,1]
	v_pk_mul_f32 v[84:85], v[84:85], v[158:159]
	v_add_u32_e32 v6, 0xc000, v5
	global_store_dwordx2 v6, v[84:85], s[80:81]
	global_load_ushort v230, v143, s[12:13] offset:2048
	global_load_ushort v231, v151, s[12:13] offset:2048
	global_load_ushort v234, v145, s[12:13] offset:2048
	global_load_ushort v235, v153, s[12:13] offset:2048
	ds_read_b64 v[12:13], v7 offset:384
	ds_read_b64 v[14:15], v8 offset:24576
	ds_read_b64 v[16:17], v8 offset:57344
	ds_read_b64 v[18:19], v9 offset:24576
	ds_read_b64 v[20:21], v9 offset:57344
	s_waitcnt lgkmcnt(5)
	v_pk_mul_f32 v[222:223], v[58:59], v[10:11] op_sel:[1,1] op_sel_hi:[1,0]
	v_pk_fma_f32 v[22:23], v[58:59], v[10:11], v[222:223] op_sel:[0,0,0] op_sel_hi:[0,1,1] neg_lo:[0,0,1]
	v_pk_mul_f32 v[222:223], v[22:23], v[22:23] op_sel:[1,1] op_sel_hi:[1,0]
	v_pk_fma_f32 v[24:25], v[22:23], v[22:23], v[222:223] op_sel:[0,0,0] op_sel_hi:[0,1,1] neg_lo:[0,0,1]
	v_pk_mul_f32 v[222:223], v[24:25], v[22:23] op_sel:[1,1] op_sel_hi:[1,0]
	v_pk_fma_f32 v[26:27], v[24:25], v[22:23], v[222:223] op_sel:[0,0,0] op_sel_hi:[0,1,1] neg_lo:[0,0,1]
	v_pk_mul_f32 v[222:223], v[62:63], v[22:23] op_sel:[1,1] op_sel_hi:[0,1]
	v_pk_fma_f32 v[28:29], v[62:63], v[22:23], v[222:223] op_sel:[0,0,0] op_sel_hi:[1,0,1] neg_hi:[0,0,1]
	v_pk_mul_f32 v[222:223], v[64:65], v[24:25] op_sel:[1,1] op_sel_hi:[0,1]
	v_pk_fma_f32 v[30:31], v[64:65], v[24:25], v[222:223] op_sel:[0,0,0] op_sel_hi:[1,0,1] neg_hi:[0,0,1]
	v_pk_mul_f32 v[222:223], v[66:67], v[26:27] op_sel:[1,1] op_sel_hi:[0,1]
	v_pk_fma_f32 v[68:69], v[66:67], v[26:27], v[222:223] op_sel:[0,0,0] op_sel_hi:[1,0,1] neg_hi:[0,0,1]
	v_pk_add_f32 v[70:71], v[60:61], v[30:31]
	v_pk_add_f32 v[72:73], v[60:61], v[30:31] neg_lo:[0,1] neg_hi:[0,1]
	v_pk_add_f32 v[74:75], v[28:29], v[68:69]
	v_pk_add_f32 v[80:81], v[28:29], v[68:69] neg_lo:[0,1] neg_hi:[0,1]
	v_pk_add_f32 v[82:83], v[70:71], v[74:75]
	v_pk_add_f32 v[84:85], v[72:73], v[80:81] op_sel:[0,1] op_sel_hi:[1,0] neg_lo:[0,1]
	s_waitcnt vmcnt(6)
; HD float2 cmul(float2 a, float2 b){ return make_float2(a.x*b.x - a.y*b.y, a.x*b.y + a.y*b.x); }
; HD float2 cmulc(float2 a, float2 b){ return make_float2(a.x*b.x + a.y*b.y, a.y*b.x - a.x*b.y); }
; HD void inv12_half(const float2* Z, const float2* twA, const float2* twB, int t, float2& x0, float2& x1){
;   float2 w1=cmul(twA[t>>6],twB[t&63]), w2=cmul(w1,w1), w3=cmul(w2,w1);
;   float2 b0=Z[t], b1=cmulc(Z[t+4096],w1), b2=cmulc(Z[t+8192],w2), b3=cmulc(Z[t+12288],w3);
;   float2 s02=make_float2(b0.x+b2.x,b0.y+b2.y), d02=make_float2(b0.x-b2.x,b0.y-b2.y);
;   float2 s13=make_float2(b1.x+b3.x,b1.y+b3.y), d13=make_float2(b1.x-b3.x,b1.y-b3.y);
;   x0=make_float2(s02.x+s13.x,s02.y+s13.y);
;   x1=make_float2(d02.x-d13.y,d02.y+d13.x);
; }
; __device__ __forceinline__ void phase_hyena(KP kp_, int hf){ asm volatile("" : "+s"(kp_)); const Params p=load_params(kp_);
;     ...
;         if (st==1){ int tq=tid; asm volatile("" : "+v"(tq));
;           _Pragma("unroll 4") for (int i=0;i<8;++i){ int tb=tq+512*i; float2 xr[2]; inv12_half(Z,twA,twB,tb,xr[0],xr[1]);
;             _Pragma("unroll") for (int hh=0;hh<2;++hh){ int t=tb+hh*4096;
;               float u0=hconv3(rv,t,wv0,wv1,wv2,bv_), u1=hconv3(rv+8192,t,wv0,wv1,wv2,bv_);
;               float x0=hconv3(r1,t,wa0,wa1,wa2,ba_), x1=hconv3(r1+8192,t,wa0,wa1,wa2,ba_);
;               float2 y=xr[hh]; y.x*=(1.f/16384.f); y.y*=(1.f/16384.f);
;               Zs[t]=make_float2(x0*(y.x+u0*bias0), x1*(y.y+u1*bias0)); } }
	v_lshlrev_b32_e32 v224, 16, v124
	v_lshlrev_b32_e32 v225, 16, v125
	v_mov_b32_e32 v226, 0
	v_mov_b32_e32 v227, 0
	v_mov_b32_e32 v170, 0
	v_mov_b32_e32 v171, 0
	v_mov_b32_dpp v226, v224 wave_shr:1 row_mask:0xf bank_mask:0xf
	v_mov_b32_dpp v227, v225 wave_shr:1 row_mask:0xf bank_mask:0xf
	v_mov_b32_dpp v170, v224 wave_shl:1 row_mask:0xf bank_mask:0xf
	v_mov_b32_dpp v171, v225 wave_shl:1 row_mask:0xf bank_mask:0xf
	v_pk_mul_f32 v[172:173], v[34:35], v[224:225]
	v_pk_fma_f32 v[172:173], v[32:33], v[226:227], v[172:173]
	v_pk_fma_f32 v[172:173], v[36:37], v[170:171], v[172:173]
	v_pk_add_f32 v[174:175], v[38:39], v[172:173]
	v_lshlrev_b32_e32 v224, 16, v242
	v_lshlrev_b32_e32 v225, 16, v243
	v_mov_b32_e32 v226, 0
	v_mov_b32_e32 v227, 0
	v_mov_b32_e32 v170, 0
	v_mov_b32_e32 v171, 0
	v_mov_b32_dpp v226, v224 wave_shr:1 row_mask:0xf bank_mask:0xf
	v_mov_b32_dpp v227, v225 wave_shr:1 row_mask:0xf bank_mask:0xf
	v_mov_b32_dpp v170, v224 wave_shl:1 row_mask:0xf bank_mask:0xf
	v_mov_b32_dpp v171, v225 wave_shl:1 row_mask:0xf bank_mask:0xf
	v_pk_mul_f32 v[172:173], v[42:43], v[224:225]
	v_pk_fma_f32 v[172:173], v[40:41], v[226:227], v[172:173]
	v_pk_fma_f32 v[172:173], v[44:45], v[170:171], v[172:173]
	v_pk_add_f32 v[156:157], v[46:47], v[172:173]
	v_lshlrev_b32_e32 v224, 16, v126
	v_lshlrev_b32_e32 v225, 16, v127
	v_mov_b32_e32 v226, 0
	v_mov_b32_e32 v227, 0
	v_mov_b32_e32 v170, 0
	v_mov_b32_e32 v171, 0
	v_mov_b32_dpp v226, v224 wave_shr:1 row_mask:0xf bank_mask:0xf
	v_mov_b32_dpp v227, v225 wave_shr:1 row_mask:0xf bank_mask:0xf
	v_mov_b32_dpp v170, v224 wave_shl:1 row_mask:0xf bank_mask:0xf
	v_mov_b32_dpp v171, v225 wave_shl:1 row_mask:0xf bank_mask:0xf
	v_pk_mul_f32 v[172:173], v[34:35], v[224:225]
	v_pk_fma_f32 v[172:173], v[32:33], v[226:227], v[172:173]
	v_pk_fma_f32 v[172:173], v[36:37], v[170:171], v[172:173]
	v_pk_add_f32 v[176:177], v[38:39], v[172:173]
	v_lshlrev_b32_e32 v224, 16, v246
	v_lshlrev_b32_e32 v225, 16, v247
	v_mov_b32_e32 v226, 0
	v_mov_b32_e32 v227, 0
	v_mov_b32_e32 v170, 0
	v_mov_b32_e32 v171, 0
	v_mov_b32_dpp v226, v224 wave_shr:1 row_mask:0xf bank_mask:0xf
	v_mov_b32_dpp v227, v225 wave_shr:1 row_mask:0xf bank_mask:0xf
	v_mov_b32_dpp v170, v224 wave_shl:1 row_mask:0xf bank_mask:0xf
	v_mov_b32_dpp v171, v225 wave_shl:1 row_mask:0xf bank_mask:0xf
	v_pk_mul_f32 v[172:173], v[42:43], v[224:225]
	v_pk_fma_f32 v[172:173], v[40:41], v[226:227], v[172:173]
	v_pk_fma_f32 v[172:173], v[44:45], v[170:171], v[172:173]
	v_pk_add_f32 v[158:159], v[46:47], v[172:173]
	v_pk_mul_f32 v[174:175], v[48:49], v[174:175]
	v_pk_fma_f32 v[82:83], v[82:83], s[66:67], v[174:175] op_sel_hi:[1,0,1]
	v_pk_mul_f32 v[82:83], v[82:83], v[156:157]
	v_add_u32_e32 v6, 0x5000, v5
	global_store_dwordx2 v6, v[82:83], s[80:81]
	v_pk_mul_f32 v[176:177], v[48:49], v[176:177]
	v_pk_fma_f32 v[84:85], v[84:85], s[66:67], v[176:177] op_sel_hi:[1,0,1]
	v_pk_mul_f32 v[84:85], v[84:85], v[158:159]
	v_add_u32_e32 v6, 0xd000, v5
	global_store_dwordx2 v6, v[84:85], s[80:81]
	global_load_ushort v242, v143, s[12:13] offset:3072
	global_load_ushort v243, v151, s[12:13] offset:3072
	global_load_ushort v246, v145, s[12:13] offset:3072
	global_load_ushort v247, v153, s[12:13] offset:3072
	ds_read_b64 v[58:59], v7 offset:448
	ds_read_b64 v[60:61], v8 offset:28672
	ds_read_b64 v[62:63], v8 offset:61440
	ds_read_b64 v[64:65], v9 offset:28672
	ds_read_b64 v[66:67], v9 offset:61440
	s_waitcnt lgkmcnt(5)
	v_pk_mul_f32 v[222:223], v[12:13], v[10:11] op_sel:[1,1] op_sel_hi:[1,0]
	v_pk_fma_f32 v[22:23], v[12:13], v[10:11], v[222:223] op_sel:[0,0,0] op_sel_hi:[0,1,1] neg_lo:[0,0,1]
	v_pk_mul_f32 v[222:223], v[22:23], v[22:23] op_sel:[1,1] op_sel_hi:[1,0]
	v_pk_fma_f32 v[24:25], v[22:23], v[22:23], v[222:223] op_sel:[0,0,0] op_sel_hi:[0,1,1] neg_lo:[0,0,1]
	v_pk_mul_f32 v[222:223], v[24:25], v[22:23] op_sel:[1,1] op_sel_hi:[1,0]
	v_pk_fma_f32 v[26:27], v[24:25], v[22:23], v[222:223] op_sel:[0,0,0] op_sel_hi:[0,1,1] neg_lo:[0,0,1]
	v_pk_mul_f32 v[222:223], v[16:17], v[22:23] op_sel:[1,1] op_sel_hi:[0,1]
	v_pk_fma_f32 v[28:29], v[16:17], v[22:23], v[222:223] op_sel:[0,0,0] op_sel_hi:[1,0,1] neg_hi:[0,0,1]
	v_pk_mul_f32 v[222:223], v[18:19], v[24:25] op_sel:[1,1] op_sel_hi:[0,1]
	v_pk_fma_f32 v[30:31], v[18:19], v[24:25], v[222:223] op_sel:[0,0,0] op_sel_hi:[1,0,1] neg_hi:[0,0,1]
	v_pk_mul_f32 v[222:223], v[20:21], v[26:27] op_sel:[1,1] op_sel_hi:[0,1]
	v_pk_fma_f32 v[68:69], v[20:21], v[26:27], v[222:223] op_sel:[0,0,0] op_sel_hi:[1,0,1] neg_hi:[0,0,1]
	v_pk_add_f32 v[70:71], v[14:15], v[30:31]
	v_pk_add_f32 v[72:73], v[14:15], v[30:31] neg_lo:[0,1] neg_hi:[0,1]
	v_pk_add_f32 v[74:75], v[28:29], v[68:69]
	v_pk_add_f32 v[80:81], v[28:29], v[68:69] neg_lo:[0,1] neg_hi:[0,1]
	v_pk_add_f32 v[82:83], v[70:71], v[74:75]
	v_pk_add_f32 v[84:85], v[72:73], v[80:81] op_sel:[0,1] op_sel_hi:[1,0] neg_lo:[0,1]
	s_waitcnt vmcnt(6)
; HD float2 cmul(float2 a, float2 b){ return make_float2(a.x*b.x - a.y*b.y, a.x*b.y + a.y*b.x); }
; HD float2 cmulc(float2 a, float2 b){ return make_float2(a.x*b.x + a.y*b.y, a.y*b.x - a.x*b.y); }
; HD void inv12_half(const float2* Z, const float2* twA, const float2* twB, int t, float2& x0, float2& x1){
;   float2 w1=cmul(twA[t>>6],twB[t&63]), w2=cmul(w1,w1), w3=cmul(w2,w1);
;   float2 b0=Z[t], b1=cmulc(Z[t+4096],w1), b2=cmulc(Z[t+8192],w2), b3=cmulc(Z[t+12288],w3);
;   float2 s02=make_float2(b0.x+b2.x,b0.y+b2.y), d02=make_float2(b0.x-b2.x,b0.y-b2.y);
;   float2 s13=make_float2(b1.x+b3.x,b1.y+b3.y), d13=make_float2(b1.x-b3.x,b1.y-b3.y);
;   x0=make_float2(s02.x+s13.x,s02.y+s13.y);
;   x1=make_float2(d02.x-d13.y,d02.y+d13.x);
; }
; __device__ __forceinline__ void phase_hyena(KP kp_, int hf){ asm volatile("" : "+s"(kp_)); const Params p=load_params(kp_);
;     ...
;         if (st==1){ int tq=tid; asm volatile("" : "+v"(tq));
;           _Pragma("unroll 4") for (int i=0;i<8;++i){ int tb=tq+512*i; float2 xr[2]; inv12_half(Z,twA,twB,tb,xr[0],xr[1]);
;             _Pragma("unroll") for (int hh=0;hh<2;++hh){ int t=tb+hh*4096;
;               float u0=hconv3(rv,t,wv0,wv1,wv2,bv_), u1=hconv3(rv+8192,t,wv0,wv1,wv2,bv_);
;               float x0=hconv3(r1,t,wa0,wa1,wa2,ba_), x1=hconv3(r1+8192,t,wa0,wa1,wa2,ba_);
;               float2 y=xr[hh]; y.x*=(1.f/16384.f); y.y*=(1.f/16384.f);
;               Zs[t]=make_float2(x0*(y.x+u0*bias0), x1*(y.y+u1*bias0)); } }
	v_lshlrev_b32_e32 v224, 16, v134
	v_lshlrev_b32_e32 v225, 16, v135
	v_mov_b32_e32 v226, 0
	v_mov_b32_e32 v227, 0
	v_mov_b32_e32 v170, 0
	v_mov_b32_e32 v171, 0
	v_mov_b32_dpp v226, v224 wave_shr:1 row_mask:0xf bank_mask:0xf
	v_mov_b32_dpp v227, v225 wave_shr:1 row_mask:0xf bank_mask:0xf
	v_mov_b32_dpp v170, v224 wave_shl:1 row_mask:0xf bank_mask:0xf
	v_mov_b32_dpp v171, v225 wave_shl:1 row_mask:0xf bank_mask:0xf
	v_pk_mul_f32 v[172:173], v[34:35], v[224:225]
	v_pk_fma_f32 v[172:173], v[32:33], v[226:227], v[172:173]
	v_pk_fma_f32 v[172:173], v[36:37], v[170:171], v[172:173]
	v_pk_add_f32 v[174:175], v[38:39], v[172:173]
	v_lshlrev_b32_e32 v224, 16, v230
	v_lshlrev_b32_e32 v225, 16, v231
	v_mov_b32_e32 v226, 0
	v_mov_b32_e32 v227, 0
	v_mov_b32_e32 v170, 0
	v_mov_b32_e32 v171, 0
	v_mov_b32_dpp v226, v224 wave_shr:1 row_mask:0xf bank_mask:0xf
	v_mov_b32_dpp v227, v225 wave_shr:1 row_mask:0xf bank_mask:0xf
	v_mov_b32_dpp v170, v224 wave_shl:1 row_mask:0xf bank_mask:0xf
	v_mov_b32_dpp v171, v225 wave_shl:1 row_mask:0xf bank_mask:0xf
	v_pk_mul_f32 v[172:173], v[42:43], v[224:225]
	v_pk_fma_f32 v[172:173], v[40:41], v[226:227], v[172:173]
	v_pk_fma_f32 v[172:173], v[44:45], v[170:171], v[172:173]
	v_pk_add_f32 v[156:157], v[46:47], v[172:173]
	v_lshlrev_b32_e32 v224, 16, v136
	v_lshlrev_b32_e32 v225, 16, v137
	v_mov_b32_e32 v226, 0
	v_mov_b32_e32 v227, 0
	v_mov_b32_e32 v170, 0
	v_mov_b32_e32 v171, 0
	v_mov_b32_dpp v226, v224 wave_shr:1 row_mask:0xf bank_mask:0xf
	v_mov_b32_dpp v227, v225 wave_shr:1 row_mask:0xf bank_mask:0xf
	v_mov_b32_dpp v170, v224 wave_shl:1 row_mask:0xf bank_mask:0xf
	v_mov_b32_dpp v171, v225 wave_shl:1 row_mask:0xf bank_mask:0xf
	v_pk_mul_f32 v[172:173], v[34:35], v[224:225]
	v_pk_fma_f32 v[172:173], v[32:33], v[226:227], v[172:173]
	v_pk_fma_f32 v[172:173], v[36:37], v[170:171], v[172:173]
	v_pk_add_f32 v[176:177], v[38:39], v[172:173]
	v_lshlrev_b32_e32 v224, 16, v234
	v_lshlrev_b32_e32 v225, 16, v235
	v_mov_b32_e32 v226, 0
	v_mov_b32_e32 v227, 0
	v_mov_b32_e32 v170, 0
	v_mov_b32_e32 v171, 0
	v_mov_b32_dpp v226, v224 wave_shr:1 row_mask:0xf bank_mask:0xf
	v_mov_b32_dpp v227, v225 wave_shr:1 row_mask:0xf bank_mask:0xf
	v_mov_b32_dpp v170, v224 wave_shl:1 row_mask:0xf bank_mask:0xf
	v_mov_b32_dpp v171, v225 wave_shl:1 row_mask:0xf bank_mask:0xf
	v_pk_mul_f32 v[172:173], v[42:43], v[224:225]
	v_pk_fma_f32 v[172:173], v[40:41], v[226:227], v[172:173]
	v_pk_fma_f32 v[172:173], v[44:45], v[170:171], v[172:173]
	v_pk_add_f32 v[158:159], v[46:47], v[172:173]
	v_pk_mul_f32 v[174:175], v[48:49], v[174:175]
	v_pk_fma_f32 v[82:83], v[82:83], s[66:67], v[174:175] op_sel_hi:[1,0,1]
	v_pk_mul_f32 v[82:83], v[82:83], v[156:157]
	v_add_u32_e32 v6, 0x6000, v5
	global_store_dwordx2 v6, v[82:83], s[80:81]
	v_pk_mul_f32 v[176:177], v[48:49], v[176:177]
	v_pk_fma_f32 v[84:85], v[84:85], s[66:67], v[176:177] op_sel_hi:[1,0,1]
	v_pk_mul_f32 v[84:85], v[84:85], v[158:159]
	v_add_u32_e32 v6, 0xe000, v5
	global_store_dwordx2 v6, v[84:85], s[80:81]
	s_waitcnt lgkmcnt(0)
; HD float2 cmul(float2 a, float2 b){ return make_float2(a.x*b.x - a.y*b.y, a.x*b.y + a.y*b.x); }
; HD float2 cmulc(float2 a, float2 b){ return make_float2(a.x*b.x + a.y*b.y, a.y*b.x - a.x*b.y); }
; HD void inv12_half(const float2* Z, const float2* twA, const float2* twB, int t, float2& x0, float2& x1){
;   float2 w1=cmul(twA[t>>6],twB[t&63]), w2=cmul(w1,w1), w3=cmul(w2,w1);
;   float2 b0=Z[t], b1=cmulc(Z[t+4096],w1), b2=cmulc(Z[t+8192],w2), b3=cmulc(Z[t+12288],w3);
;   float2 s02=make_float2(b0.x+b2.x,b0.y+b2.y), d02=make_float2(b0.x-b2.x,b0.y-b2.y);
;   float2 s13=make_float2(b1.x+b3.x,b1.y+b3.y), d13=make_float2(b1.x-b3.x,b1.y-b3.y);
;   x0=make_float2(s02.x+s13.x,s02.y+s13.y);
;   x1=make_float2(d02.x-d13.y,d02.y+d13.x);
; }
; __device__ __forceinline__ void phase_hyena(KP kp_, int hf){ asm volatile("" : "+s"(kp_)); const Params p=load_params(kp_);
;     ...
;         if (st==1){ int tq=tid; asm volatile("" : "+v"(tq));
;           _Pragma("unroll 4") for (int i=0;i<8;++i){ int tb=tq+512*i; float2 xr[2]; inv12_half(Z,twA,twB,tb,xr[0],xr[1]);
;             _Pragma("unroll") for (int hh=0;hh<2;++hh){ int t=tb+hh*4096;
;               float u0=hconv3(rv,t,wv0,wv1,wv2,bv_), u1=hconv3(rv+8192,t,wv0,wv1,wv2,bv_);
;               float x0=hconv3(r1,t,wa0,wa1,wa2,ba_), x1=hconv3(r1+8192,t,wa0,wa1,wa2,ba_);
;               float2 y=xr[hh]; y.x*=(1.f/16384.f); y.y*=(1.f/16384.f);
;               Zs[t]=make_float2(x0*(y.x+u0*bias0), x1*(y.y+u1*bias0)); } }
	v_pk_mul_f32 v[222:223], v[58:59], v[10:11] op_sel:[1,1] op_sel_hi:[1,0]
	v_pk_fma_f32 v[22:23], v[58:59], v[10:11], v[222:223] op_sel:[0,0,0] op_sel_hi:[0,1,1] neg_lo:[0,0,1]
	v_pk_mul_f32 v[222:223], v[22:23], v[22:23] op_sel:[1,1] op_sel_hi:[1,0]
	v_pk_fma_f32 v[24:25], v[22:23], v[22:23], v[222:223] op_sel:[0,0,0] op_sel_hi:[0,1,1] neg_lo:[0,0,1]
	v_pk_mul_f32 v[222:223], v[24:25], v[22:23] op_sel:[1,1] op_sel_hi:[1,0]
	v_pk_fma_f32 v[26:27], v[24:25], v[22:23], v[222:223] op_sel:[0,0,0] op_sel_hi:[0,1,1] neg_lo:[0,0,1]
	v_pk_mul_f32 v[222:223], v[62:63], v[22:23] op_sel:[1,1] op_sel_hi:[0,1]
	v_pk_fma_f32 v[28:29], v[62:63], v[22:23], v[222:223] op_sel:[0,0,0] op_sel_hi:[1,0,1] neg_hi:[0,0,1]
	v_pk_mul_f32 v[222:223], v[64:65], v[24:25] op_sel:[1,1] op_sel_hi:[0,1]
	v_pk_fma_f32 v[30:31], v[64:65], v[24:25], v[222:223] op_sel:[0,0,0] op_sel_hi:[1,0,1] neg_hi:[0,0,1]
	v_pk_mul_f32 v[222:223], v[66:67], v[26:27] op_sel:[1,1] op_sel_hi:[0,1]
	v_pk_fma_f32 v[68:69], v[66:67], v[26:27], v[222:223] op_sel:[0,0,0] op_sel_hi:[1,0,1] neg_hi:[0,0,1]
	v_pk_add_f32 v[70:71], v[60:61], v[30:31]
	v_pk_add_f32 v[72:73], v[60:61], v[30:31] neg_lo:[0,1] neg_hi:[0,1]
	v_pk_add_f32 v[74:75], v[28:29], v[68:69]
	v_pk_add_f32 v[80:81], v[28:29], v[68:69] neg_lo:[0,1] neg_hi:[0,1]
	v_pk_add_f32 v[82:83], v[70:71], v[74:75]
	v_pk_add_f32 v[84:85], v[72:73], v[80:81] op_sel:[0,1] op_sel_hi:[1,0] neg_lo:[0,1]
	s_waitcnt vmcnt(2)
	v_lshlrev_b32_e32 v224, 16, v138
	v_lshlrev_b32_e32 v225, 16, v139
	v_mov_b32_e32 v226, 0
	v_mov_b32_e32 v227, 0
	v_mov_b32_e32 v170, 0
	v_mov_b32_e32 v171, 0
	v_mov_b32_dpp v226, v224 wave_shr:1 row_mask:0xf bank_mask:0xf
	v_mov_b32_dpp v227, v225 wave_shr:1 row_mask:0xf bank_mask:0xf
	v_mov_b32_dpp v170, v224 wave_shl:1 row_mask:0xf bank_mask:0xf
	v_mov_b32_dpp v171, v225 wave_shl:1 row_mask:0xf bank_mask:0xf
	v_pk_mul_f32 v[172:173], v[34:35], v[224:225]
	v_pk_fma_f32 v[172:173], v[32:33], v[226:227], v[172:173]
	v_pk_fma_f32 v[172:173], v[36:37], v[170:171], v[172:173]
	v_pk_add_f32 v[174:175], v[38:39], v[172:173]
	v_lshlrev_b32_e32 v224, 16, v242
	v_lshlrev_b32_e32 v225, 16, v243
	v_mov_b32_e32 v226, 0
	v_mov_b32_e32 v227, 0
	v_mov_b32_e32 v170, 0
	v_mov_b32_e32 v171, 0
	v_mov_b32_dpp v226, v224 wave_shr:1 row_mask:0xf bank_mask:0xf
	v_mov_b32_dpp v227, v225 wave_shr:1 row_mask:0xf bank_mask:0xf
	v_mov_b32_dpp v170, v224 wave_shl:1 row_mask:0xf bank_mask:0xf
	v_mov_b32_dpp v171, v225 wave_shl:1 row_mask:0xf bank_mask:0xf
	v_pk_mul_f32 v[172:173], v[42:43], v[224:225]
	v_pk_fma_f32 v[172:173], v[40:41], v[226:227], v[172:173]
	v_pk_fma_f32 v[172:173], v[44:45], v[170:171], v[172:173]
	v_pk_add_f32 v[156:157], v[46:47], v[172:173]
	v_lshlrev_b32_e32 v224, 16, v140
	v_lshlrev_b32_e32 v225, 16, v141
	v_mov_b32_e32 v226, 0
	v_mov_b32_e32 v227, 0
	v_mov_b32_e32 v170, 0
	v_mov_b32_e32 v171, 0
	v_mov_b32_dpp v226, v224 wave_shr:1 row_mask:0xf bank_mask:0xf
	v_mov_b32_dpp v227, v225 wave_shr:1 row_mask:0xf bank_mask:0xf
	v_mov_b32_dpp v170, v224 wave_shl:1 row_mask:0xf bank_mask:0xf
	v_mov_b32_dpp v171, v225 wave_shl:1 row_mask:0xf bank_mask:0xf
	v_pk_mul_f32 v[172:173], v[34:35], v[224:225]
	v_pk_fma_f32 v[172:173], v[32:33], v[226:227], v[172:173]
	v_pk_fma_f32 v[172:173], v[36:37], v[170:171], v[172:173]
	v_pk_add_f32 v[176:177], v[38:39], v[172:173]
	v_lshlrev_b32_e32 v224, 16, v246
	v_lshlrev_b32_e32 v225, 16, v247
	v_mov_b32_e32 v226, 0
	v_mov_b32_e32 v227, 0
	v_mov_b32_e32 v170, 0
	v_mov_b32_e32 v171, 0
	v_mov_b32_dpp v226, v224 wave_shr:1 row_mask:0xf bank_mask:0xf
	v_mov_b32_dpp v227, v225 wave_shr:1 row_mask:0xf bank_mask:0xf
	v_mov_b32_dpp v170, v224 wave_shl:1 row_mask:0xf bank_mask:0xf
	v_mov_b32_dpp v171, v225 wave_shl:1 row_mask:0xf bank_mask:0xf
	v_pk_mul_f32 v[172:173], v[42:43], v[224:225]
	v_pk_fma_f32 v[172:173], v[40:41], v[226:227], v[172:173]
	v_pk_fma_f32 v[172:173], v[44:45], v[170:171], v[172:173]
	v_pk_add_f32 v[158:159], v[46:47], v[172:173]
	v_pk_mul_f32 v[174:175], v[48:49], v[174:175]
	v_pk_fma_f32 v[82:83], v[82:83], s[66:67], v[174:175] op_sel_hi:[1,0,1]
	v_pk_mul_f32 v[82:83], v[82:83], v[156:157]
	v_add_u32_e32 v6, 0x7000, v5
	global_store_dwordx2 v6, v[82:83], s[80:81]
	v_pk_mul_f32 v[176:177], v[48:49], v[176:177]
	v_pk_fma_f32 v[84:85], v[84:85], s[66:67], v[176:177] op_sel_hi:[1,0,1]
	v_pk_mul_f32 v[84:85], v[84:85], v[158:159]
	v_add_u32_e32 v6, 0xf000, v5
	global_store_dwordx2 v6, v[84:85], s[80:81]
	s_mov_b32 s12, 0x8000
